# hoist second-half ss loads in P7 KVB/QB epilogues, residual-load hoist in P11 epilogues, FFN-up ss cache across units
# speedup vs baseline: 1.0030x; 1.0021x over previous
.LBB0_1321:
	s_lshl_b32 s27, s6, 8
	s_add_i32 s27, s27, s62
	v_or_b32_e32 v142, s27, v1
	v_ashrrev_i32_e32 v143, 31, v142
	v_lshl_add_u64 v[140:141], v[142:143], 2, s[18:19]
	global_load_dword v151, v[140:141], off
	global_load_dword v158, v[140:141], off offset:64
	global_load_dword v159, v[140:141], off offset:128
	global_load_dword v160, v[140:141], off offset:192
	v_add_u32_e32 v246, s27, v145
	v_ashrrev_i32_e32 v247, 31, v246
	v_lshl_add_u64 v[246:247], v[246:247], 2, s[18:19]
	global_load_dword v238, v[246:247], off
	global_load_dword v239, v[246:247], off offset:64
	global_load_dword v240, v[246:247], off offset:128
	global_load_dword v241, v[246:247], off offset:192
	v_lshlrev_b64 v[156:157], 12, v[142:143]
	v_lshl_or_b32 v140, s0, 8, v146
	v_ashrrev_i32_e32 v141, 31, v140
	v_or_b32_e32 v152, 16, v142
	v_lshlrev_b64 v[140:141], 1, v[140:141]
	v_ashrrev_i32_e32 v153, 31, v152
	v_lshl_add_u64 v[156:157], s[16:17], 0, v[156:157]
	v_or_b32_e32 v154, 32, v142
	v_lshlrev_b64 v[152:153], 12, v[152:153]
	v_lshl_add_u64 v[156:157], v[156:157], 0, v[140:141]
	v_ashrrev_i32_e32 v155, 31, v154
	v_lshl_add_u64 v[152:153], s[16:17], 0, v[152:153]
	v_lshlrev_b64 v[154:155], 12, v[154:155]
	v_lshl_add_u64 v[152:153], v[152:153], 0, v[140:141]
	v_lshl_add_u64 v[154:155], s[16:17], 0, v[154:155]
	v_lshl_add_u64 v[154:155], v[154:155], 0, v[140:141]
	s_waitcnt vmcnt(4)
	v_fmamk_f32 v143, v151, 0x3b800000, v150
	v_fmamk_f32 v151, v158, 0x3b800000, v150
	v_fmamk_f32 v158, v159, 0x3b800000, v150
	v_fmamk_f32 v159, v160, 0x3b800000, v150
	v_mul_f32_e32 v160, 0x4b800000, v143
	v_mul_f32_e32 v161, 0x4b800000, v151
	v_mul_f32_e32 v162, 0x4b800000, v158
	v_cmp_gt_f32_e32 vcc, s67, v143
	v_cmp_gt_f32_e64 s[0:1], s67, v151
	v_cmp_gt_f32_e64 s[6:7], s67, v158
	v_mul_f32_e32 v163, 0x4b800000, v159
	v_cndmask_b32_e32 v143, v143, v160, vcc
	v_cndmask_b32_e64 v151, v151, v161, s[0:1]
	v_cndmask_b32_e64 v158, v158, v162, s[6:7]
	v_cmp_gt_f32_e64 s[8:9], s67, v159
	v_rsq_f32_e32 v143, v143
	v_rsq_f32_e32 v151, v151
	v_cndmask_b32_e64 v159, v159, v163, s[8:9]
	v_rsq_f32_e32 v161, v158
	v_rsq_f32_e32 v159, v159
	v_mul_f32_e32 v158, 0x45800000, v143
	v_mul_f32_e32 v160, 0x45800000, v151
	v_mul_f32_e32 v162, 0x45800000, v161
	v_mul_f32_e32 v163, 0x45800000, v159
	v_cndmask_b32_e32 v158, v143, v158, vcc
	v_cndmask_b32_e64 v160, v151, v160, s[0:1]
	v_cndmask_b32_e64 v162, v161, v162, s[6:7]
	v_pk_mul_f32 v[128:129], v[128:129], v[158:159] op_sel_hi:[1,0]
	v_pk_mul_f32 v[126:127], v[126:127], v[158:159] op_sel_hi:[1,0]
	v_pk_mul_f32 v[120:121], v[120:121], v[160:161] op_sel_hi:[1,0]
	v_pk_mul_f32 v[118:119], v[118:119], v[160:161] op_sel_hi:[1,0]
	v_pk_mul_f32 v[116:117], v[116:117], v[160:161] op_sel_hi:[1,0]
	v_pk_mul_f32 v[114:115], v[114:115], v[160:161] op_sel_hi:[1,0]
	v_pk_mul_f32 v[96:97], v[96:97], v[160:161] op_sel_hi:[1,0]
	v_pk_mul_f32 v[94:95], v[94:95], v[160:161] op_sel_hi:[1,0]
	v_pk_mul_f32 v[92:93], v[92:93], v[160:161] op_sel_hi:[1,0]
	v_pk_mul_f32 v[90:91], v[90:91], v[160:161] op_sel_hi:[1,0]
	v_pk_mul_f32 v[160:161], v[84:85], v[162:163] op_sel_hi:[1,0]
	v_cvt_pk_bf16_f32 v84, v126, v127
	v_cvt_pk_bf16_f32 v85, v128, v129
	v_cndmask_b32_e64 v164, v159, v163, s[8:9]
	v_pk_mul_f32 v[124:125], v[124:125], v[158:159] op_sel_hi:[1,0]
	v_pk_mul_f32 v[122:123], v[122:123], v[158:159] op_sel_hi:[1,0]
	v_pk_mul_f32 v[108:109], v[108:109], v[158:159] op_sel_hi:[1,0]
	v_pk_mul_f32 v[106:107], v[106:107], v[158:159] op_sel_hi:[1,0]
	v_pk_mul_f32 v[104:105], v[104:105], v[158:159] op_sel_hi:[1,0]
	v_pk_mul_f32 v[102:103], v[102:103], v[158:159] op_sel_hi:[1,0]
	v_pk_mul_f32 v[158:159], v[86:87], v[162:163] op_sel_hi:[1,0]
	v_cvt_pk_bf16_f32 v86, v122, v123
	v_cvt_pk_bf16_f32 v87, v124, v125
	global_store_dwordx4 v[156:157], v[84:87], off
	v_pk_mul_f32 v[112:113], v[112:113], v[162:163] op_sel_hi:[1,0]
	v_pk_mul_f32 v[110:111], v[110:111], v[162:163] op_sel_hi:[1,0]
	v_cvt_pk_bf16_f32 v84, v106, v107
	v_cvt_pk_bf16_f32 v85, v108, v109
	v_cvt_pk_bf16_f32 v86, v102, v103
	v_cvt_pk_bf16_f32 v87, v104, v105
	global_store_dwordx4 v[156:157], v[84:87], off offset:256
	v_pk_mul_f32 v[100:101], v[100:101], v[162:163] op_sel_hi:[1,0]
	v_pk_mul_f32 v[98:99], v[98:99], v[162:163] op_sel_hi:[1,0]
	v_cvt_pk_bf16_f32 v84, v118, v119
	v_cvt_pk_bf16_f32 v85, v120, v121
	v_cvt_pk_bf16_f32 v86, v114, v115
	v_cvt_pk_bf16_f32 v87, v116, v117
	global_store_dwordx4 v[152:153], v[84:87], off
	v_pk_mul_f32 v[88:89], v[88:89], v[162:163] op_sel_hi:[1,0]
	v_pk_mul_f32 v[80:81], v[80:81], v[164:165] op_sel_hi:[1,0]
	v_cvt_pk_bf16_f32 v84, v94, v95
	v_cvt_pk_bf16_f32 v85, v96, v97
	v_cvt_pk_bf16_f32 v86, v90, v91
	v_cvt_pk_bf16_f32 v87, v92, v93
	global_store_dwordx4 v[152:153], v[84:87], off offset:256
	v_pk_mul_f32 v[78:79], v[78:79], v[164:165] op_sel_hi:[1,0]
	v_pk_mul_f32 v[70:71], v[70:71], v[164:165] op_sel_hi:[1,0]
	v_cvt_pk_bf16_f32 v84, v110, v111
	v_cvt_pk_bf16_f32 v85, v112, v113
	v_cvt_pk_bf16_f32 v86, v98, v99
	v_cvt_pk_bf16_f32 v87, v100, v101
	global_store_dwordx4 v[154:155], v[84:87], off
	v_pk_mul_f32 v[72:73], v[72:73], v[164:165] op_sel_hi:[1,0]
	s_nop 0
	v_pk_mul_f32 v[84:85], v[82:83], v[162:163] op_sel_hi:[1,0]
	v_cvt_pk_bf16_f32 v82, v158, v159
	v_cvt_pk_bf16_f32 v83, v88, v89
	s_nop 0
	v_cvt_pk_bf16_f32 v84, v84, v85
	v_cvt_pk_bf16_f32 v85, v160, v161
	global_store_dwordx4 v[154:155], v[82:85], off offset:256
	s_nop 1
	v_or_b32_e32 v82, 48, v142
	v_ashrrev_i32_e32 v83, 31, v82
	v_lshlrev_b64 v[82:83], 12, v[82:83]
	v_lshl_add_u64 v[82:83], s[16:17], 0, v[82:83]
	v_lshl_add_u64 v[82:83], v[82:83], 0, v[140:141]
	v_pk_mul_f32 v[84:85], v[76:77], v[164:165] op_sel_hi:[1,0]
	v_pk_mul_f32 v[76:77], v[74:75], v[164:165] op_sel_hi:[1,0]
	v_cvt_pk_bf16_f32 v74, v78, v79
	v_cvt_pk_bf16_f32 v75, v80, v81
	s_nop 0
	v_cvt_pk_bf16_f32 v76, v76, v77
	v_cvt_pk_bf16_f32 v77, v84, v85
	global_store_dwordx4 v[82:83], v[74:77], off
	s_nop 1
	v_pk_mul_f32 v[74:75], v[68:69], v[164:165] op_sel_hi:[1,0]
	v_pk_mul_f32 v[68:69], v[66:67], v[164:165] op_sel_hi:[1,0]
	v_cvt_pk_bf16_f32 v66, v70, v71
	v_cvt_pk_bf16_f32 v67, v72, v73
	s_nop 0
	v_cvt_pk_bf16_f32 v68, v68, v69
	v_cvt_pk_bf16_f32 v69, v74, v75
	global_store_dwordx4 v[82:83], v[66:69], off offset:256
	s_nop 1
	v_add_u32_e32 v66, s27, v145
	v_ashrrev_i32_e32 v67, 31, v66
	v_lshlrev_b64 v[70:71], 12, v[66:67]
	v_or_b32_e32 v68, 16, v66
	v_ashrrev_i32_e32 v69, 31, v68
	v_lshl_add_u64 v[70:71], s[16:17], 0, v[70:71]
	v_lshlrev_b64 v[68:69], 12, v[68:69]
	v_lshl_add_u64 v[70:71], v[70:71], 0, v[140:141]
	v_lshl_add_u64 v[68:69], s[16:17], 0, v[68:69]
	v_lshl_add_u64 v[68:69], v[68:69], 0, v[140:141]
	s_waitcnt vmcnt(8)
	v_fmamk_f32 v67, v238, 0x3b800000, v150
	v_fmamk_f32 v72, v239, 0x3b800000, v150
	v_fmamk_f32 v73, v240, 0x3b800000, v150
	v_fmamk_f32 v74, v241, 0x3b800000, v150
	v_mul_f32_e32 v75, 0x4b800000, v67
	v_cmp_gt_f32_e32 vcc, s67, v67
	v_mul_f32_e32 v77, 0x4b800000, v73
	v_cmp_gt_f32_e64 s[6:7], s67, v73
	v_cndmask_b32_e32 v67, v67, v75, vcc
	v_mul_f32_e32 v76, 0x4b800000, v72
	v_cmp_gt_f32_e64 s[0:1], s67, v72
	v_cndmask_b32_e64 v73, v73, v77, s[6:7]
	v_rsq_f32_e32 v67, v67
	v_cndmask_b32_e64 v72, v72, v76, s[0:1]
	v_rsq_f32_e32 v73, v73
	v_rsq_f32_e32 v75, v72
	v_mul_f32_e32 v78, 0x4b800000, v74
	v_cmp_gt_f32_e64 s[8:9], s67, v74
	v_mul_f32_e32 v72, 0x45800000, v67
	v_mul_f32_e32 v76, 0x45800000, v73
	v_cndmask_b32_e64 v74, v74, v78, s[8:9]
	v_cndmask_b32_e32 v72, v67, v72, vcc
	v_rsq_f32_e32 v77, v74
	v_mul_f32_e32 v74, 0x45800000, v75
	v_cndmask_b32_e64 v76, v73, v76, s[6:7]
	v_pk_mul_f32 v[64:65], v[64:65], v[72:73] op_sel_hi:[1,0]
	v_pk_mul_f32 v[62:63], v[62:63], v[72:73] op_sel_hi:[1,0]
	v_pk_mul_f32 v[60:61], v[60:61], v[72:73] op_sel_hi:[1,0]
	v_pk_mul_f32 v[58:59], v[58:59], v[72:73] op_sel_hi:[1,0]
	v_pk_mul_f32 v[48:49], v[48:49], v[72:73] op_sel_hi:[1,0]
	v_pk_mul_f32 v[46:47], v[46:47], v[72:73] op_sel_hi:[1,0]
	v_pk_mul_f32 v[80:81], v[44:45], v[72:73] op_sel_hi:[1,0]
	v_pk_mul_f32 v[72:73], v[42:43], v[72:73] op_sel_hi:[1,0]
	v_cvt_pk_bf16_f32 v42, v62, v63
	v_cvt_pk_bf16_f32 v43, v64, v65
	v_cndmask_b32_e64 v74, v75, v74, s[0:1]
	v_cvt_pk_bf16_f32 v44, v58, v59
	v_cvt_pk_bf16_f32 v45, v60, v61
	global_store_dwordx4 v[70:71], v[42:45], off
	v_pk_mul_f32 v[56:57], v[56:57], v[74:75] op_sel_hi:[1,0]
	v_pk_mul_f32 v[54:55], v[54:55], v[74:75] op_sel_hi:[1,0]
	v_cvt_pk_bf16_f32 v42, v46, v47
	v_cvt_pk_bf16_f32 v43, v48, v49
	v_cvt_pk_bf16_f32 v44, v72, v73
	v_cvt_pk_bf16_f32 v45, v80, v81
	global_store_dwordx4 v[70:71], v[42:45], off offset:256
	v_pk_mul_f32 v[52:53], v[52:53], v[74:75] op_sel_hi:[1,0]
	v_pk_mul_f32 v[50:51], v[50:51], v[74:75] op_sel_hi:[1,0]
	v_cvt_pk_bf16_f32 v42, v54, v55
	v_cvt_pk_bf16_f32 v43, v56, v57
	v_pk_mul_f32 v[38:39], v[38:39], v[74:75] op_sel_hi:[1,0]
	v_cvt_pk_bf16_f32 v44, v50, v51
	v_cvt_pk_bf16_f32 v45, v52, v53
	global_store_dwordx4 v[68:69], v[42:45], off
	v_pk_mul_f32 v[40:41], v[40:41], v[74:75] op_sel_hi:[1,0]
	v_pk_mul_f32 v[32:33], v[32:33], v[76:77] op_sel_hi:[1,0]
	v_pk_mul_f32 v[42:43], v[36:37], v[74:75] op_sel_hi:[1,0]
	v_pk_mul_f32 v[36:37], v[34:35], v[74:75] op_sel_hi:[1,0]
	v_cvt_pk_bf16_f32 v34, v38, v39
	v_cvt_pk_bf16_f32 v35, v40, v41
	v_pk_mul_f32 v[30:31], v[30:31], v[76:77] op_sel_hi:[1,0]
	v_cvt_pk_bf16_f32 v36, v36, v37
	v_cvt_pk_bf16_f32 v37, v42, v43
	global_store_dwordx4 v[68:69], v[34:37], off offset:256
	v_pk_mul_f32 v[22:23], v[22:23], v[76:77] op_sel_hi:[1,0]
	v_pk_mul_f32 v[24:25], v[24:25], v[76:77] op_sel_hi:[1,0]
	v_or_b32_e32 v34, 32, v66
	v_ashrrev_i32_e32 v35, 31, v34
	v_lshlrev_b64 v[34:35], 12, v[34:35]
	v_lshl_add_u64 v[34:35], s[16:17], 0, v[34:35]
	v_lshl_add_u64 v[34:35], v[34:35], 0, v[140:141]
	v_pk_mul_f32 v[36:37], v[28:29], v[76:77] op_sel_hi:[1,0]
	v_pk_mul_f32 v[28:29], v[26:27], v[76:77] op_sel_hi:[1,0]
	v_cvt_pk_bf16_f32 v26, v30, v31
	v_cvt_pk_bf16_f32 v27, v32, v33
	v_mul_f32_e32 v78, 0x45800000, v77
	v_cvt_pk_bf16_f32 v28, v28, v29
	v_cvt_pk_bf16_f32 v29, v36, v37
	global_store_dwordx4 v[34:35], v[26:29], off
	v_cndmask_b32_e64 v78, v77, v78, s[8:9]
	v_pk_mul_f32 v[16:17], v[16:17], v[78:79] op_sel_hi:[1,0]
	v_pk_mul_f32 v[26:27], v[20:21], v[76:77] op_sel_hi:[1,0]
	v_pk_mul_f32 v[20:21], v[18:19], v[76:77] op_sel_hi:[1,0]
	v_cvt_pk_bf16_f32 v18, v22, v23
	v_cvt_pk_bf16_f32 v19, v24, v25
	v_pk_mul_f32 v[14:15], v[14:15], v[78:79] op_sel_hi:[1,0]
	v_cvt_pk_bf16_f32 v20, v20, v21
	v_cvt_pk_bf16_f32 v21, v26, v27
	global_store_dwordx4 v[34:35], v[18:21], off offset:256
	v_pk_mul_f32 v[8:9], v[8:9], v[78:79] op_sel_hi:[1,0]
	v_pk_mul_f32 v[6:7], v[6:7], v[78:79] op_sel_hi:[1,0]
	v_or_b32_e32 v18, 48, v66
	v_ashrrev_i32_e32 v19, 31, v18
	v_lshlrev_b64 v[18:19], 12, v[18:19]
	v_lshl_add_u64 v[18:19], s[16:17], 0, v[18:19]
	v_lshl_add_u64 v[18:19], v[18:19], 0, v[140:141]
	v_pk_mul_f32 v[20:21], v[12:13], v[78:79] op_sel_hi:[1,0]
	v_pk_mul_f32 v[12:13], v[10:11], v[78:79] op_sel_hi:[1,0]
	v_cvt_pk_bf16_f32 v10, v14, v15
	v_cvt_pk_bf16_f32 v11, v16, v17
	s_andn2_b64 vcc, exec, s[30:31]
	v_cvt_pk_bf16_f32 v12, v12, v13
	v_cvt_pk_bf16_f32 v13, v20, v21
	global_store_dwordx4 v[18:19], v[10:13], off
	s_mov_b64 s[0:1], -1
	s_nop 0
	v_pk_mul_f32 v[10:11], v[4:5], v[78:79] op_sel_hi:[1,0]
	v_pk_mul_f32 v[4:5], v[2:3], v[78:79] op_sel_hi:[1,0]
	v_cvt_pk_bf16_f32 v2, v6, v7
	v_cvt_pk_bf16_f32 v3, v8, v9
	s_nop 0
	v_cvt_pk_bf16_f32 v4, v4, v5
	v_cvt_pk_bf16_f32 v5, v10, v11
	global_store_dwordx4 v[18:19], v[2:5], off offset:256
	s_cbranch_vccnz .LBB0_1305
	s_andn2_b64 vcc, exec, s[14:15]
	s_cbranch_vccnz .LBB0_1304
	s_barrier
	s_branch .LBB0_1304

.LBB0_1343:
	ds_read_b128 v[144:147], v153
	ds_read_b128 v[158:161], v153 offset:1024
	ds_read_b128 v[162:165], v153 offset:2048
	ds_read_b128 v[166:169], v153 offset:3072
	ds_read_b128 v[170:173], v154
	ds_read_b128 v[174:177], v154 offset:1024
	ds_read_b128 v[178:181], v154 offset:2048
	ds_read_b128 v[184:187], v154 offset:3072
	s_add_u32 s6, s0, 0x100
	s_addc_u32 s7, s1, 0
	s_cmp_eq_u32 s52, 2
	s_cselect_b32 s27, s19, s7
	s_cselect_b32 s26, s18, s6
	s_cselect_b32 s9, s25, s51
	s_cselect_b32 s8, s24, s50
	v_lshl_add_u64 v[148:149], s[0:1], 0, v[138:139]
	s_add_i32 m0, s34, 0xc000
	ds_read_b128 v[188:191], v155
	ds_read_b128 v[192:195], v155 offset:1024
	ds_read_b128 v[196:199], v155 offset:2048
	ds_read_b128 v[200:203], v155 offset:3072
	ds_read_b128 v[204:207], v155 offset:4096
	ds_read_b128 v[208:211], v155 offset:5120
	ds_read_b128 v[212:215], v155 offset:6144
	ds_read_b128 v[216:219], v155 offset:7168
	global_load_lds_dwordx4 v[148:149], off
	v_lshl_add_u64 v[148:149], s[0:1], 0, v[140:141]
	s_add_i32 m0, s34, 0xe000
	s_nop 0
	global_load_lds_dwordx4 v[148:149], off
	s_waitcnt vmcnt(8)
	s_waitcnt lgkmcnt(0)
	s_barrier
	s_setprio 1
	s_waitcnt lgkmcnt(0)
	v_mfma_f32_16x16x32_bf16 v[126:129], v[144:147], v[188:191], v[126:129]
	v_mfma_f32_16x16x32_bf16 v[122:125], v[162:165], v[188:191], v[122:125]
	v_mfma_f32_16x16x32_bf16 v[118:121], v[144:147], v[196:199], v[118:121]
	v_mfma_f32_16x16x32_bf16 v[114:117], v[162:165], v[196:199], v[114:117]
	v_mfma_f32_16x16x32_bf16 v[110:113], v[144:147], v[204:207], v[110:113]
	v_mfma_f32_16x16x32_bf16 v[98:101], v[162:165], v[204:207], v[98:101]
	v_mfma_f32_16x16x32_bf16 v[82:85], v[144:147], v[212:215], v[82:85]
	v_mfma_f32_16x16x32_bf16 v[74:77], v[162:165], v[212:215], v[74:77]
	v_mfma_f32_16x16x32_bf16 v[126:129], v[158:161], v[192:195], v[126:129]
	v_mfma_f32_16x16x32_bf16 v[122:125], v[166:169], v[192:195], v[122:125]
	v_mfma_f32_16x16x32_bf16 v[118:121], v[158:161], v[200:203], v[118:121]
	v_mfma_f32_16x16x32_bf16 v[114:117], v[166:169], v[200:203], v[114:117]
	v_mfma_f32_16x16x32_bf16 v[110:113], v[158:161], v[208:211], v[110:113]
	v_mfma_f32_16x16x32_bf16 v[98:101], v[166:169], v[208:211], v[98:101]
	v_mfma_f32_16x16x32_bf16 v[82:85], v[158:161], v[216:219], v[82:85]
	v_mfma_f32_16x16x32_bf16 v[74:77], v[166:169], v[216:219], v[74:77]
	s_setprio 0
	s_setprio 1
	v_mfma_f32_16x16x32_bf16 v[106:109], v[170:173], v[188:191], v[106:109]
	v_mfma_f32_16x16x32_bf16 v[102:105], v[178:181], v[188:191], v[102:105]
	v_mfma_f32_16x16x32_bf16 v[94:97], v[170:173], v[196:199], v[94:97]
	v_mfma_f32_16x16x32_bf16 v[90:93], v[178:181], v[196:199], v[90:93]
	v_mfma_f32_16x16x32_bf16 v[86:89], v[170:173], v[204:207], v[86:89]
	v_mfma_f32_16x16x32_bf16 v[78:81], v[178:181], v[204:207], v[78:81]
	v_mfma_f32_16x16x32_bf16 v[70:73], v[170:173], v[212:215], v[70:73]
	v_mfma_f32_16x16x32_bf16 v[66:69], v[178:181], v[212:215], v[66:69]
	v_mfma_f32_16x16x32_bf16 v[106:109], v[174:177], v[192:195], v[106:109]
	v_mfma_f32_16x16x32_bf16 v[102:105], v[184:187], v[192:195], v[102:105]
	v_mfma_f32_16x16x32_bf16 v[94:97], v[174:177], v[200:203], v[94:97]
	v_mfma_f32_16x16x32_bf16 v[90:93], v[184:187], v[200:203], v[90:93]
	v_mfma_f32_16x16x32_bf16 v[86:89], v[174:177], v[208:211], v[86:89]
	v_mfma_f32_16x16x32_bf16 v[78:81], v[184:187], v[208:211], v[78:81]
	v_mfma_f32_16x16x32_bf16 v[70:73], v[174:177], v[216:219], v[70:73]
	v_mfma_f32_16x16x32_bf16 v[66:69], v[184:187], v[216:219], v[66:69]
	s_setprio 0
	s_barrier
	s_add_i32 s0, s42, s5
	v_lshl_add_u64 v[148:149], s[8:9], 0, v[132:133]
	s_mov_b32 m0, s0
	ds_read_b128 v[188:191], v155 offset:16384
	ds_read_b128 v[192:195], v155 offset:17408
	ds_read_b128 v[196:199], v155 offset:18432
	ds_read_b128 v[200:203], v155 offset:19456
	ds_read_b128 v[204:207], v155 offset:20480
	ds_read_b128 v[208:211], v155 offset:21504
	ds_read_b128 v[212:215], v155 offset:22528
	ds_read_b128 v[216:219], v155 offset:23552
	global_load_lds_dwordx4 v[148:149], off
	s_add_i32 m0, s0, 0x2000
	s_add_u32 s0, s8, 0x18000
	v_lshl_add_u64 v[220:221], s[8:9], 0, v[136:137]
	s_addc_u32 s1, s9, 0
	s_add_i32 s53, s43, s5
	global_load_lds_dwordx4 v[220:221], off
	v_lshl_add_u64 v[222:223], s[0:1], 0, v[132:133]
	s_mov_b32 m0, s53
	v_lshl_add_u64 v[224:225], s[26:27], 0, v[134:135]
	global_load_lds_dwordx4 v[222:223], off
	v_lshl_add_u64 v[222:223], s[0:1], 0, v[136:137]
	s_add_i32 m0, s53, 0x2000
	s_nop 0
	global_load_lds_dwordx4 v[222:223], off
	v_lshl_add_u64 v[222:223], s[26:27], 0, v[130:131]
	s_mov_b32 m0, s34
	s_nop 0
	global_load_lds_dwordx4 v[222:223], off
	s_mov_b32 m0, s35
	s_nop 0
	global_load_lds_dwordx4 v[224:225], off
	s_waitcnt vmcnt(8)
	s_waitcnt lgkmcnt(0)
	s_barrier
	s_setprio 1
	s_waitcnt lgkmcnt(0)
	v_mfma_f32_16x16x32_bf16 v[62:65], v[144:147], v[188:191], v[62:65]
	v_mfma_f32_16x16x32_bf16 v[58:61], v[162:165], v[188:191], v[58:61]
	v_mfma_f32_16x16x32_bf16 v[54:57], v[144:147], v[196:199], v[54:57]
	v_mfma_f32_16x16x32_bf16 v[46:49], v[162:165], v[196:199], v[46:49]
	v_mfma_f32_16x16x32_bf16 v[34:37], v[144:147], v[204:207], v[34:37]
	v_mfma_f32_16x16x32_bf16 v[26:29], v[162:165], v[204:207], v[26:29]
	v_mfma_f32_16x16x32_bf16 v[18:21], v[144:147], v[212:215], v[18:21]
	v_mfma_f32_16x16x32_bf16 v[10:13], v[162:165], v[212:215], v[10:13]
	v_mfma_f32_16x16x32_bf16 v[62:65], v[158:161], v[192:195], v[62:65]
	v_mfma_f32_16x16x32_bf16 v[58:61], v[166:169], v[192:195], v[58:61]
	v_mfma_f32_16x16x32_bf16 v[54:57], v[158:161], v[200:203], v[54:57]
	v_mfma_f32_16x16x32_bf16 v[46:49], v[166:169], v[200:203], v[46:49]
	v_mfma_f32_16x16x32_bf16 v[34:37], v[158:161], v[208:211], v[34:37]
	v_mfma_f32_16x16x32_bf16 v[26:29], v[166:169], v[208:211], v[26:29]
	v_mfma_f32_16x16x32_bf16 v[18:21], v[158:161], v[216:219], v[18:21]
	v_mfma_f32_16x16x32_bf16 v[10:13], v[166:169], v[216:219], v[10:13]
	s_setprio 0
	s_setprio 1
	v_mfma_f32_16x16x32_bf16 v[50:53], v[170:173], v[188:191], v[50:53]
	v_mfma_f32_16x16x32_bf16 v[42:45], v[178:181], v[188:191], v[42:45]
	v_mfma_f32_16x16x32_bf16 v[38:41], v[170:173], v[196:199], v[38:41]
	v_mfma_f32_16x16x32_bf16 v[30:33], v[178:181], v[196:199], v[30:33]
	v_mfma_f32_16x16x32_bf16 v[22:25], v[170:173], v[204:207], v[22:25]
	v_mfma_f32_16x16x32_bf16 v[14:17], v[178:181], v[204:207], v[14:17]
	v_mfma_f32_16x16x32_bf16 v[6:9], v[170:173], v[212:215], v[6:9]
	v_mfma_f32_16x16x32_bf16 v[2:5], v[178:181], v[212:215], v[2:5]
	v_mfma_f32_16x16x32_bf16 v[50:53], v[174:177], v[192:195], v[50:53]
	v_mfma_f32_16x16x32_bf16 v[42:45], v[184:187], v[192:195], v[42:45]
	v_mfma_f32_16x16x32_bf16 v[38:41], v[174:177], v[200:203], v[38:41]
	v_mfma_f32_16x16x32_bf16 v[30:33], v[184:187], v[200:203], v[30:33]
	v_mfma_f32_16x16x32_bf16 v[22:25], v[174:177], v[208:211], v[22:25]
	v_mfma_f32_16x16x32_bf16 v[14:17], v[184:187], v[208:211], v[14:17]
	v_mfma_f32_16x16x32_bf16 v[6:9], v[174:177], v[216:219], v[6:9]
	v_mfma_f32_16x16x32_bf16 v[2:5], v[184:187], v[216:219], v[2:5]
	s_setprio 0
	s_barrier
	s_add_i32 s53, 0, 0x18000
	v_add_u32_e32 v157, s53, v150
	s_add_i32 s54, 0, 0x1c000
	ds_read_b128 v[144:147], v157
	ds_read_b128 v[158:161], v157 offset:1024
	ds_read_b128 v[162:165], v157 offset:2048
	ds_read_b128 v[166:169], v157 offset:3072
	v_add_u32_e32 v157, s54, v150
	ds_read_b128 v[170:173], v157
	ds_read_b128 v[174:177], v157 offset:1024
	ds_read_b128 v[178:181], v157 offset:2048
	ds_read_b128 v[184:187], v157 offset:3072
	s_add_u32 s0, s26, 0x18000
	s_addc_u32 s1, s27, 0
	s_mov_b32 m0, s36
	v_lshl_add_u64 v[226:227], s[0:1], 0, v[130:131]
	ds_read_b128 v[188:191], v155 offset:32768
	ds_read_b128 v[192:195], v155 offset:33792
	ds_read_b128 v[196:199], v155 offset:34816
	ds_read_b128 v[200:203], v155 offset:35840
	ds_read_b128 v[204:207], v155 offset:36864
	ds_read_b128 v[208:211], v155 offset:37888
	ds_read_b128 v[212:215], v155 offset:38912
	ds_read_b128 v[216:219], v155 offset:39936
	global_load_lds_dwordx4 v[226:227], off
	v_lshl_add_u64 v[226:227], s[0:1], 0, v[134:135]
	s_mov_b32 m0, s37
	s_nop 0
	global_load_lds_dwordx4 v[226:227], off
	s_waitcnt vmcnt(8)
	s_waitcnt lgkmcnt(0)
	s_barrier
	s_setprio 1
	s_waitcnt lgkmcnt(0)
	v_mfma_f32_16x16x32_bf16 v[126:129], v[144:147], v[188:191], v[126:129]
	v_mfma_f32_16x16x32_bf16 v[122:125], v[162:165], v[188:191], v[122:125]
	v_mfma_f32_16x16x32_bf16 v[118:121], v[144:147], v[196:199], v[118:121]
	v_mfma_f32_16x16x32_bf16 v[114:117], v[162:165], v[196:199], v[114:117]
	v_mfma_f32_16x16x32_bf16 v[110:113], v[144:147], v[204:207], v[110:113]
	v_mfma_f32_16x16x32_bf16 v[98:101], v[162:165], v[204:207], v[98:101]
	v_mfma_f32_16x16x32_bf16 v[82:85], v[144:147], v[212:215], v[82:85]
	v_mfma_f32_16x16x32_bf16 v[74:77], v[162:165], v[212:215], v[74:77]
	v_mfma_f32_16x16x32_bf16 v[126:129], v[158:161], v[192:195], v[126:129]
	v_mfma_f32_16x16x32_bf16 v[122:125], v[166:169], v[192:195], v[122:125]
	v_mfma_f32_16x16x32_bf16 v[118:121], v[158:161], v[200:203], v[118:121]
	v_mfma_f32_16x16x32_bf16 v[114:117], v[166:169], v[200:203], v[114:117]
	v_mfma_f32_16x16x32_bf16 v[110:113], v[158:161], v[208:211], v[110:113]
	v_mfma_f32_16x16x32_bf16 v[98:101], v[166:169], v[208:211], v[98:101]
	v_mfma_f32_16x16x32_bf16 v[82:85], v[158:161], v[216:219], v[82:85]
	v_mfma_f32_16x16x32_bf16 v[74:77], v[166:169], v[216:219], v[74:77]
	s_setprio 0
	s_setprio 1
	v_mfma_f32_16x16x32_bf16 v[106:109], v[170:173], v[188:191], v[106:109]
	v_mfma_f32_16x16x32_bf16 v[102:105], v[178:181], v[188:191], v[102:105]
	v_mfma_f32_16x16x32_bf16 v[94:97], v[170:173], v[196:199], v[94:97]
	v_mfma_f32_16x16x32_bf16 v[90:93], v[178:181], v[196:199], v[90:93]
	v_mfma_f32_16x16x32_bf16 v[86:89], v[170:173], v[204:207], v[86:89]
	v_mfma_f32_16x16x32_bf16 v[78:81], v[178:181], v[204:207], v[78:81]
	v_mfma_f32_16x16x32_bf16 v[70:73], v[170:173], v[212:215], v[70:73]
	v_mfma_f32_16x16x32_bf16 v[66:69], v[178:181], v[212:215], v[66:69]
	v_mfma_f32_16x16x32_bf16 v[106:109], v[174:177], v[192:195], v[106:109]
	v_mfma_f32_16x16x32_bf16 v[102:105], v[184:187], v[192:195], v[102:105]
	v_mfma_f32_16x16x32_bf16 v[94:97], v[174:177], v[200:203], v[94:97]
	v_mfma_f32_16x16x32_bf16 v[90:93], v[184:187], v[200:203], v[90:93]
	v_mfma_f32_16x16x32_bf16 v[86:89], v[174:177], v[208:211], v[86:89]
	v_mfma_f32_16x16x32_bf16 v[78:81], v[184:187], v[208:211], v[78:81]
	v_mfma_f32_16x16x32_bf16 v[70:73], v[174:177], v[216:219], v[70:73]
	v_mfma_f32_16x16x32_bf16 v[66:69], v[184:187], v[216:219], v[66:69]
	s_setprio 0
	s_barrier
	s_add_i32 s0, s53, s5
	v_lshl_add_u64 v[148:149], v[148:149], 0, s[16:17]
	s_mov_b32 m0, s0
	ds_read_b128 v[188:191], v155 offset:49152
	ds_read_b128 v[192:195], v155 offset:50176
	ds_read_b128 v[196:199], v155 offset:51200
	ds_read_b128 v[200:203], v155 offset:52224
	ds_read_b128 v[204:207], v155 offset:53248
	ds_read_b128 v[208:211], v155 offset:54272
	ds_read_b128 v[212:215], v155 offset:55296
	ds_read_b128 v[216:219], v155 offset:56320
	global_load_lds_dwordx4 v[148:149], off
	s_add_i32 m0, s0, 0x2000
	s_add_u32 s0, s8, 0x18080
	v_lshl_add_u64 v[148:149], v[220:221], 0, s[16:17]
	s_addc_u32 s1, s9, 0
	s_add_i32 s8, s54, s5
	global_load_lds_dwordx4 v[148:149], off
	v_lshl_add_u64 v[148:149], s[0:1], 0, v[132:133]
	s_mov_b32 m0, s8
	s_nop 0
	global_load_lds_dwordx4 v[148:149], off
	v_lshl_add_u64 v[148:149], s[0:1], 0, v[136:137]
	s_add_i32 m0, s8, 0x2000
	s_nop 0
	global_load_lds_dwordx4 v[148:149], off
	v_lshl_add_u64 v[148:149], v[222:223], 0, s[16:17]
	s_mov_b32 m0, s40
	s_nop 0
	global_load_lds_dwordx4 v[148:149], off
	v_lshl_add_u64 v[148:149], v[224:225], 0, s[16:17]
	s_mov_b32 m0, s41
	s_nop 0
	global_load_lds_dwordx4 v[148:149], off
	s_waitcnt vmcnt(8)
	s_waitcnt lgkmcnt(0)
	s_barrier
	s_setprio 1
	s_waitcnt lgkmcnt(0)
	v_mfma_f32_16x16x32_bf16 v[62:65], v[144:147], v[188:191], v[62:65]
	v_mfma_f32_16x16x32_bf16 v[58:61], v[162:165], v[188:191], v[58:61]
	v_mfma_f32_16x16x32_bf16 v[54:57], v[144:147], v[196:199], v[54:57]
	v_mfma_f32_16x16x32_bf16 v[46:49], v[162:165], v[196:199], v[46:49]
	v_mfma_f32_16x16x32_bf16 v[34:37], v[144:147], v[204:207], v[34:37]
	v_mfma_f32_16x16x32_bf16 v[26:29], v[162:165], v[204:207], v[26:29]
	v_mfma_f32_16x16x32_bf16 v[18:21], v[144:147], v[212:215], v[18:21]
	v_mfma_f32_16x16x32_bf16 v[10:13], v[162:165], v[212:215], v[10:13]
	v_mfma_f32_16x16x32_bf16 v[62:65], v[158:161], v[192:195], v[62:65]
	v_mfma_f32_16x16x32_bf16 v[58:61], v[166:169], v[192:195], v[58:61]
	v_mfma_f32_16x16x32_bf16 v[54:57], v[158:161], v[200:203], v[54:57]
	v_mfma_f32_16x16x32_bf16 v[46:49], v[166:169], v[200:203], v[46:49]
	v_mfma_f32_16x16x32_bf16 v[34:37], v[158:161], v[208:211], v[34:37]
	v_mfma_f32_16x16x32_bf16 v[26:29], v[166:169], v[208:211], v[26:29]
	v_mfma_f32_16x16x32_bf16 v[18:21], v[158:161], v[216:219], v[18:21]
	v_mfma_f32_16x16x32_bf16 v[10:13], v[166:169], v[216:219], v[10:13]
	s_setprio 0
	s_setprio 1
	v_mfma_f32_16x16x32_bf16 v[50:53], v[170:173], v[188:191], v[50:53]
	v_mfma_f32_16x16x32_bf16 v[42:45], v[178:181], v[188:191], v[42:45]
	v_mfma_f32_16x16x32_bf16 v[38:41], v[170:173], v[196:199], v[38:41]
	v_mfma_f32_16x16x32_bf16 v[30:33], v[178:181], v[196:199], v[30:33]
	v_mfma_f32_16x16x32_bf16 v[22:25], v[170:173], v[204:207], v[22:25]
	v_mfma_f32_16x16x32_bf16 v[14:17], v[178:181], v[204:207], v[14:17]
	v_mfma_f32_16x16x32_bf16 v[6:9], v[170:173], v[212:215], v[6:9]
	v_mfma_f32_16x16x32_bf16 v[2:5], v[178:181], v[212:215], v[2:5]
	v_mfma_f32_16x16x32_bf16 v[50:53], v[174:177], v[192:195], v[50:53]
	v_mfma_f32_16x16x32_bf16 v[42:45], v[184:187], v[192:195], v[42:45]
	v_mfma_f32_16x16x32_bf16 v[38:41], v[174:177], v[200:203], v[38:41]
	v_mfma_f32_16x16x32_bf16 v[30:33], v[184:187], v[200:203], v[30:33]
	v_mfma_f32_16x16x32_bf16 v[22:25], v[174:177], v[208:211], v[22:25]
	v_mfma_f32_16x16x32_bf16 v[14:17], v[184:187], v[208:211], v[14:17]
	v_mfma_f32_16x16x32_bf16 v[6:9], v[174:177], v[216:219], v[6:9]
	v_mfma_f32_16x16x32_bf16 v[2:5], v[184:187], v[216:219], v[2:5]
	s_setprio 0
	s_barrier
	s_add_i32 s52, s52, 2
	s_add_u32 s50, s50, 0x100
	s_addc_u32 s51, s51, 0
	s_cmp_gt_u32 s52, 3
	s_mov_b64 s[0:1], s[6:7]
	s_cbranch_scc0 .LBB0_1343
	s_lshl_b32 s26, s49, 8
	s_add_i32 s26, s26, s39
	v_or_b32_e32 v148, s26, v1
	v_ashrrev_i32_e32 v149, 31, v148
	v_lshl_add_u64 v[144:145], v[148:149], 2, s[14:15]
	global_load_dword v149, v[144:145], off
	global_load_dword v157, v[144:145], off offset:64
	global_load_dword v164, v[144:145], off offset:128
	global_load_dword v165, v[144:145], off offset:192
	v_add_u32_e32 v246, s26, v151
	v_ashrrev_i32_e32 v247, 31, v246
	v_lshl_add_u64 v[246:247], v[246:247], 2, s[14:15]
	global_load_dword v238, v[246:247], off
	global_load_dword v239, v[246:247], off offset:64
	global_load_dword v240, v[246:247], off offset:128
	global_load_dword v241, v[246:247], off offset:192
	v_mov_b64_e32 v[144:145], s[12:13]
	v_or_b32_e32 v160, 16, v148
	v_or_b32_e32 v162, 32, v148
	v_mad_i64_i32 v[158:159], s[0:1], v148, s45, v[144:145]
	v_mad_i64_i32 v[160:161], s[0:1], v160, s45, v[144:145]
	v_mad_i64_i32 v[162:163], s[0:1], v162, s45, v[144:145]
	v_lshl_or_b32 v146, s48, 8, v152
	v_ashrrev_i32_e32 v147, 31, v146
	v_lshlrev_b64 v[146:147], 1, v[146:147]
	v_lshl_add_u64 v[158:159], v[158:159], 0, v[146:147]
	v_lshl_add_u64 v[160:161], v[160:161], 0, v[146:147]
	v_lshl_add_u64 v[162:163], v[162:163], 0, v[146:147]
	s_mov_b32 s48, s46
	s_mov_b32 s49, s47
	s_waitcnt vmcnt(4)
	v_fmamk_f32 v149, v149, 0x3b2aaaab, v156
	v_fmamk_f32 v157, v157, 0x3b2aaaab, v156
	v_fmamk_f32 v164, v164, 0x3b2aaaab, v156
	v_fmamk_f32 v165, v165, 0x3b2aaaab, v156
	v_mul_f32_e32 v166, 0x4b800000, v149
	v_mul_f32_e32 v167, 0x4b800000, v157
	v_mul_f32_e32 v168, 0x4b800000, v164
	v_cmp_gt_f32_e32 vcc, s44, v149
	v_cmp_gt_f32_e64 s[0:1], s44, v157
	v_cmp_gt_f32_e64 s[6:7], s44, v164
	v_mul_f32_e32 v169, 0x4b800000, v165
	v_cndmask_b32_e32 v149, v149, v166, vcc
	v_cndmask_b32_e64 v157, v157, v167, s[0:1]
	v_cndmask_b32_e64 v164, v164, v168, s[6:7]
	v_cmp_gt_f32_e64 s[8:9], s44, v165
	v_rsq_f32_e32 v149, v149
	v_rsq_f32_e32 v157, v157
	v_cndmask_b32_e64 v165, v165, v169, s[8:9]
	v_rsq_f32_e32 v164, v164
	v_rsq_f32_e32 v165, v165
	v_mul_f32_e32 v166, 0x45800000, v149
	v_mul_f32_e32 v167, 0x45800000, v157
	v_mul_f32_e32 v168, 0x45800000, v164
	v_mul_f32_e32 v169, 0x45800000, v165
	v_cndmask_b32_e32 v149, v149, v166, vcc
	v_cndmask_b32_e64 v157, v157, v167, s[0:1]
	v_cndmask_b32_e64 v167, v164, v168, s[6:7]
	v_cndmask_b32_e64 v165, v165, v169, s[8:9]
	v_mul_f32_e32 v164, 0x3dd53b94, v149
	v_mul_f32_e32 v166, 0x3dd53b94, v157
	v_mul_f32_e32 v168, 0x3dd53b94, v167
	v_mul_f32_e32 v170, 0x3dd53b94, v165
	v_pk_mul_f32 v[128:129], v[128:129], v[164:165] op_sel_hi:[1,0]
	v_pk_mul_f32 v[126:127], v[126:127], v[164:165] op_sel_hi:[1,0]
	v_pk_mul_f32 v[124:125], v[124:125], v[164:165] op_sel_hi:[1,0]
	v_pk_mul_f32 v[122:123], v[122:123], v[164:165] op_sel_hi:[1,0]
	v_pk_mul_f32 v[108:109], v[108:109], v[164:165] op_sel_hi:[1,0]
	v_pk_mul_f32 v[106:107], v[106:107], v[164:165] op_sel_hi:[1,0]
	v_pk_mul_f32 v[104:105], v[104:105], v[164:165] op_sel_hi:[1,0]
	v_pk_mul_f32 v[102:103], v[102:103], v[164:165] op_sel_hi:[1,0]
	v_pk_mul_f32 v[120:121], v[120:121], v[166:167] op_sel_hi:[1,0]
	v_pk_mul_f32 v[118:119], v[118:119], v[166:167] op_sel_hi:[1,0]
	v_pk_mul_f32 v[116:117], v[116:117], v[166:167] op_sel_hi:[1,0]
	v_pk_mul_f32 v[114:115], v[114:115], v[166:167] op_sel_hi:[1,0]
	v_pk_mul_f32 v[96:97], v[96:97], v[166:167] op_sel_hi:[1,0]
	v_pk_mul_f32 v[94:95], v[94:95], v[166:167] op_sel_hi:[1,0]
	v_pk_mul_f32 v[92:93], v[92:93], v[166:167] op_sel_hi:[1,0]
	v_pk_mul_f32 v[164:165], v[90:91], v[166:167] op_sel_hi:[1,0]
	v_pk_mul_f32 v[166:167], v[88:89], v[168:169] op_sel_hi:[1,0]
	v_cvt_pk_bf16_f32 v88, v126, v127
	v_cvt_pk_bf16_f32 v89, v128, v129
	v_cvt_pk_bf16_f32 v90, v122, v123
	v_cvt_pk_bf16_f32 v91, v124, v125
	global_store_dwordx4 v[158:159], v[88:91], off
	v_pk_mul_f32 v[112:113], v[112:113], v[168:169] op_sel_hi:[1,0]
	v_pk_mul_f32 v[110:111], v[110:111], v[168:169] op_sel_hi:[1,0]
	v_cvt_pk_bf16_f32 v88, v106, v107
	v_cvt_pk_bf16_f32 v89, v108, v109
	v_cvt_pk_bf16_f32 v90, v102, v103
	v_cvt_pk_bf16_f32 v91, v104, v105
	global_store_dwordx4 v[158:159], v[88:91], off offset:256
	v_pk_mul_f32 v[100:101], v[100:101], v[168:169] op_sel_hi:[1,0]
	v_pk_mul_f32 v[98:99], v[98:99], v[168:169] op_sel_hi:[1,0]
	v_cvt_pk_bf16_f32 v88, v118, v119
	v_cvt_pk_bf16_f32 v89, v120, v121
	v_cvt_pk_bf16_f32 v90, v114, v115
	v_cvt_pk_bf16_f32 v91, v116, v117
	global_store_dwordx4 v[160:161], v[88:91], off
	v_pk_mul_f32 v[86:87], v[86:87], v[168:169] op_sel_hi:[1,0]
	v_pk_mul_f32 v[82:83], v[82:83], v[170:171] op_sel_hi:[1,0]
	v_cvt_pk_bf16_f32 v88, v94, v95
	v_cvt_pk_bf16_f32 v89, v96, v97
	v_cvt_pk_bf16_f32 v90, v164, v165
	v_cvt_pk_bf16_f32 v91, v92, v93
	global_store_dwordx4 v[160:161], v[88:91], off offset:256
	v_pk_mul_f32 v[70:71], v[70:71], v[170:171] op_sel_hi:[1,0]
	v_pk_mul_f32 v[72:73], v[72:73], v[170:171] op_sel_hi:[1,0]
	v_cvt_pk_bf16_f32 v88, v110, v111
	v_cvt_pk_bf16_f32 v89, v112, v113
	v_cvt_pk_bf16_f32 v90, v98, v99
	v_cvt_pk_bf16_f32 v91, v100, v101
	global_store_dwordx4 v[162:163], v[88:91], off
	s_nop 1
	v_pk_mul_f32 v[88:89], v[80:81], v[168:169] op_sel_hi:[1,0]
	v_pk_mul_f32 v[80:81], v[78:79], v[168:169] op_sel_hi:[1,0]
	v_cvt_pk_bf16_f32 v78, v86, v87
	v_cvt_pk_bf16_f32 v79, v166, v167
	s_nop 0
	v_cvt_pk_bf16_f32 v80, v80, v81
	v_cvt_pk_bf16_f32 v81, v88, v89
	global_store_dwordx4 v[162:163], v[78:81], off offset:256
	s_nop 1
	v_or_b32_e32 v78, 48, v148
	v_mad_i64_i32 v[78:79], s[0:1], v78, s45, v[144:145]
	v_lshl_add_u64 v[78:79], v[78:79], 0, v[146:147]
	v_pk_mul_f32 v[80:81], v[84:85], v[170:171] op_sel_hi:[1,0]
	v_pk_mul_f32 v[84:85], v[76:77], v[170:171] op_sel_hi:[1,0]
	v_pk_mul_f32 v[76:77], v[74:75], v[170:171] op_sel_hi:[1,0]
	v_cvt_pk_bf16_f32 v74, v82, v83
	v_cvt_pk_bf16_f32 v75, v80, v81
	s_nop 0
	v_cvt_pk_bf16_f32 v76, v76, v77
	v_cvt_pk_bf16_f32 v77, v84, v85
	global_store_dwordx4 v[78:79], v[74:77], off
	s_nop 1
	v_pk_mul_f32 v[74:75], v[68:69], v[170:171] op_sel_hi:[1,0]
	v_pk_mul_f32 v[68:69], v[66:67], v[170:171] op_sel_hi:[1,0]
	v_cvt_pk_bf16_f32 v66, v70, v71
	v_cvt_pk_bf16_f32 v67, v72, v73
	s_nop 0
	v_cvt_pk_bf16_f32 v68, v68, v69
	v_cvt_pk_bf16_f32 v69, v74, v75
	global_store_dwordx4 v[78:79], v[66:69], off offset:256
	s_nop 1
	v_add_u32_e32 v66, s26, v151
	v_ashrrev_i32_e32 v67, 31, v66
	v_or_b32_e32 v70, 16, v66
	v_mad_i64_i32 v[68:69], s[0:1], v66, s45, v[144:145]
	v_mad_i64_i32 v[70:71], s[0:1], v70, s45, v[144:145]
	v_lshl_add_u64 v[68:69], v[68:69], 0, v[146:147]
	v_lshl_add_u64 v[70:71], v[70:71], 0, v[146:147]
	s_waitcnt vmcnt(8)
	v_fmamk_f32 v67, v238, 0x3b2aaaab, v156
	v_fmamk_f32 v72, v239, 0x3b2aaaab, v156
	v_fmamk_f32 v73, v240, 0x3b2aaaab, v156
	v_mul_f32_e32 v75, 0x4b800000, v67
	v_cmp_gt_f32_e32 vcc, s44, v67
	v_mul_f32_e32 v76, 0x4b800000, v72
	v_mul_f32_e32 v77, 0x4b800000, v73
	v_cndmask_b32_e32 v67, v67, v75, vcc
	v_cmp_gt_f32_e64 s[0:1], s44, v72
	v_cmp_gt_f32_e64 s[6:7], s44, v73
	v_fmamk_f32 v74, v241, 0x3b2aaaab, v156
	v_cndmask_b32_e64 v72, v72, v76, s[0:1]
	v_cndmask_b32_e64 v73, v73, v77, s[6:7]
	v_rsq_f32_e32 v67, v67
	v_mul_f32_e32 v78, 0x4b800000, v74
	v_cmp_gt_f32_e64 s[8:9], s44, v74
	v_rsq_f32_e32 v72, v72
	v_rsq_f32_e32 v73, v73
	v_cndmask_b32_e64 v74, v74, v78, s[8:9]
	v_rsq_f32_e32 v74, v74
	v_mul_f32_e32 v75, 0x45800000, v67
	v_mul_f32_e32 v76, 0x45800000, v72
	v_mul_f32_e32 v77, 0x45800000, v73
	v_cndmask_b32_e32 v67, v67, v75, vcc
	v_cndmask_b32_e64 v75, v72, v76, s[0:1]
	v_cndmask_b32_e64 v73, v73, v77, s[6:7]
	v_mul_f32_e32 v72, 0x3dd53b94, v67
	v_mul_f32_e32 v78, 0x45800000, v74
	v_mul_f32_e32 v76, 0x3dd53b94, v73
	v_pk_mul_f32 v[64:65], v[64:65], v[72:73] op_sel_hi:[1,0]
	v_pk_mul_f32 v[62:63], v[62:63], v[72:73] op_sel_hi:[1,0]
	v_pk_mul_f32 v[60:61], v[60:61], v[72:73] op_sel_hi:[1,0]
	v_pk_mul_f32 v[58:59], v[58:59], v[72:73] op_sel_hi:[1,0]
	v_pk_mul_f32 v[52:53], v[52:53], v[72:73] op_sel_hi:[1,0]
	v_pk_mul_f32 v[50:51], v[50:51], v[72:73] op_sel_hi:[1,0]
	v_pk_mul_f32 v[80:81], v[44:45], v[72:73] op_sel_hi:[1,0]
	v_pk_mul_f32 v[72:73], v[42:43], v[72:73] op_sel_hi:[1,0]
	v_cvt_pk_bf16_f32 v42, v62, v63
	v_cvt_pk_bf16_f32 v43, v64, v65
	v_cvt_pk_bf16_f32 v44, v58, v59
	v_cvt_pk_bf16_f32 v45, v60, v61
	v_cndmask_b32_e64 v77, v74, v78, s[8:9]
	v_mul_f32_e32 v74, 0x3dd53b94, v75
	global_store_dwordx4 v[68:69], v[42:45], off
	v_pk_mul_f32 v[56:57], v[56:57], v[74:75] op_sel_hi:[1,0]
	v_pk_mul_f32 v[54:55], v[54:55], v[74:75] op_sel_hi:[1,0]
	v_cvt_pk_bf16_f32 v42, v50, v51
	v_cvt_pk_bf16_f32 v43, v52, v53
	v_cvt_pk_bf16_f32 v44, v72, v73
	v_cvt_pk_bf16_f32 v45, v80, v81
	global_store_dwordx4 v[68:69], v[42:45], off offset:256
	v_pk_mul_f32 v[48:49], v[48:49], v[74:75] op_sel_hi:[1,0]
	v_pk_mul_f32 v[38:39], v[38:39], v[74:75] op_sel_hi:[1,0]
	v_pk_mul_f32 v[44:45], v[46:47], v[74:75] op_sel_hi:[1,0]
	v_cvt_pk_bf16_f32 v42, v54, v55
	v_cvt_pk_bf16_f32 v43, v56, v57
	v_pk_mul_f32 v[40:41], v[40:41], v[74:75] op_sel_hi:[1,0]
	v_cvt_pk_bf16_f32 v44, v44, v45
	v_cvt_pk_bf16_f32 v45, v48, v49
	global_store_dwordx4 v[70:71], v[42:45], off
	v_pk_mul_f32 v[34:35], v[34:35], v[76:77] op_sel_hi:[1,0]
	v_pk_mul_f32 v[22:23], v[22:23], v[76:77] op_sel_hi:[1,0]
	v_pk_mul_f32 v[42:43], v[32:33], v[74:75] op_sel_hi:[1,0]
	v_pk_mul_f32 v[32:33], v[30:31], v[74:75] op_sel_hi:[1,0]
	v_cvt_pk_bf16_f32 v30, v38, v39
	v_cvt_pk_bf16_f32 v31, v40, v41
	v_pk_mul_f32 v[24:25], v[24:25], v[76:77] op_sel_hi:[1,0]
	v_cvt_pk_bf16_f32 v32, v32, v33
	v_cvt_pk_bf16_f32 v33, v42, v43
	global_store_dwordx4 v[70:71], v[30:33], off offset:256
	v_mul_f32_e32 v78, 0x3dd53b94, v77
	v_pk_mul_f32 v[18:19], v[18:19], v[78:79] op_sel_hi:[1,0]
	v_or_b32_e32 v30, 32, v66
	v_mad_i64_i32 v[30:31], s[0:1], v30, s45, v[144:145]
	v_lshl_add_u64 v[30:31], v[30:31], 0, v[146:147]
	v_pk_mul_f32 v[32:33], v[36:37], v[76:77] op_sel_hi:[1,0]
	v_pk_mul_f32 v[36:37], v[28:29], v[76:77] op_sel_hi:[1,0]
	v_pk_mul_f32 v[28:29], v[26:27], v[76:77] op_sel_hi:[1,0]
	v_cvt_pk_bf16_f32 v26, v34, v35
	v_cvt_pk_bf16_f32 v27, v32, v33
	v_pk_mul_f32 v[8:9], v[8:9], v[78:79] op_sel_hi:[1,0]
	v_cvt_pk_bf16_f32 v28, v28, v29
	v_cvt_pk_bf16_f32 v29, v36, v37
	global_store_dwordx4 v[30:31], v[26:29], off
	v_pk_mul_f32 v[6:7], v[6:7], v[78:79] op_sel_hi:[1,0]
	s_and_b64 vcc, exec, s[20:21]
	v_pk_mul_f32 v[26:27], v[16:17], v[76:77] op_sel_hi:[1,0]
	v_pk_mul_f32 v[16:17], v[14:15], v[76:77] op_sel_hi:[1,0]
	v_cvt_pk_bf16_f32 v14, v22, v23
	v_cvt_pk_bf16_f32 v15, v24, v25
	s_mov_b32 s20, s46
	v_cvt_pk_bf16_f32 v16, v16, v17
	v_cvt_pk_bf16_f32 v17, v26, v27
	global_store_dwordx4 v[30:31], v[14:17], off offset:256
	s_mov_b32 s21, s47
	s_mov_b64 s[6:7], s[24:25]
	v_or_b32_e32 v14, 48, v66
	v_mad_i64_i32 v[14:15], s[0:1], v14, s45, v[144:145]
	v_lshl_add_u64 v[14:15], v[14:15], 0, v[146:147]
	v_pk_mul_f32 v[16:17], v[20:21], v[78:79] op_sel_hi:[1,0]
	v_pk_mul_f32 v[20:21], v[12:13], v[78:79] op_sel_hi:[1,0]
	v_pk_mul_f32 v[12:13], v[10:11], v[78:79] op_sel_hi:[1,0]
	v_cvt_pk_bf16_f32 v10, v18, v19
	v_cvt_pk_bf16_f32 v11, v16, v17
	s_mov_b64 s[0:1], s[18:19]
	v_cvt_pk_bf16_f32 v12, v12, v13
	v_cvt_pk_bf16_f32 v13, v20, v21
	global_store_dwordx4 v[14:15], v[10:13], off
	s_nop 1
	v_pk_mul_f32 v[10:11], v[4:5], v[78:79] op_sel_hi:[1,0]
	v_pk_mul_f32 v[4:5], v[2:3], v[78:79] op_sel_hi:[1,0]
	v_cvt_pk_bf16_f32 v2, v6, v7
	v_cvt_pk_bf16_f32 v3, v8, v9
	s_nop 0
	v_cvt_pk_bf16_f32 v4, v4, v5
	v_cvt_pk_bf16_f32 v5, v10, v11
	global_store_dwordx4 v[14:15], v[2:5], off offset:256
	s_cbranch_vccz .LBB0_1335
	s_branch .LBB0_1349

.LBB0_1925:
	v_lshl_add_u32 v166, s38, 8, v180
	v_lshl_or_b32 v128, s40, 8, v183
	v_ashrrev_i32_e32 v167, 31, v166
	v_ashrrev_i32_e32 v129, 31, v128
	v_lshlrev_b64 v[130:131], 11, v[166:167]
	v_lshl_add_u64 v[130:131], s[12:13], 0, v[130:131]
	v_lshlrev_b64 v[164:165], 1, v[128:129]
	v_lshl_add_u64 v[196:197], v[130:131], 0, v[164:165]
	global_load_dwordx4 v[188:191], v[196:197], off
	global_load_dwordx4 v[192:195], v[196:197], off offset:256
	v_or_b32_e32 v176, 16, v166
	v_or_b32_e32 v172, 32, v166
	v_or_b32_e32 v168, 48, v166
	v_ashrrev_i32_e32 v177, 31, v176
	v_ashrrev_i32_e32 v173, 31, v172
	v_ashrrev_i32_e32 v169, 31, v168
	v_lshlrev_b64 v[128:129], 11, v[176:177]
	v_lshlrev_b64 v[130:131], 11, v[172:173]
	v_lshlrev_b64 v[132:133], 11, v[168:169]
	v_lshl_add_u64 v[128:129], s[12:13], 0, v[128:129]
	v_lshl_add_u64 v[130:131], s[12:13], 0, v[130:131]
	v_lshl_add_u64 v[132:133], s[12:13], 0, v[132:133]
	v_lshl_add_u64 v[178:179], v[128:129], 0, v[164:165]
	v_lshl_add_u64 v[174:175], v[130:131], 0, v[164:165]
	v_lshl_add_u64 v[170:171], v[132:133], 0, v[164:165]
	global_load_dwordx4 v[148:151], v[178:179], off
	global_load_dwordx4 v[144:147], v[178:179], off offset:256
	global_load_dwordx4 v[140:143], v[174:175], off
	global_load_dwordx4 v[136:139], v[174:175], off offset:256
	global_load_dwordx4 v[132:135], v[170:171], off
	global_load_dwordx4 v[128:131], v[170:171], off offset:256
	s_mov_b64 s[98:99], 0x40000
	v_lshl_add_u64 v[234:235], v[196:197], 0, s[98:99]
	global_load_dwordx4 v[210:213], v[234:235], off
	global_load_dwordx4 v[214:217], v[234:235], off offset:256
	v_lshl_add_u64 v[234:235], v[178:179], 0, s[98:99]
	global_load_dwordx4 v[218:221], v[234:235], off
	global_load_dwordx4 v[222:225], v[234:235], off offset:256
	v_lshl_add_u64 v[234:235], v[174:175], 0, s[98:99]
	global_load_dwordx4 v[226:229], v[234:235], off
	global_load_dwordx4 v[230:233], v[234:235], off offset:256
	v_lshl_add_u64 v[234:235], v[170:171], 0, s[98:99]
	global_load_dwordx4 v[238:241], v[234:235], off
	global_load_dwordx4 v[242:245], v[234:235], off offset:256
	v_and_b32_e32 v187, 64, v185
	v_xor_b32_e32 v186, 16, v185
	v_add_u32_e32 v187, 64, v187
	v_xor_b32_e32 v198, 32, v185
	v_cmp_lt_i32_e32 vcc, v186, v187
	s_waitcnt vmcnt(8)
	v_and_b32_e32 v199, 0xffff0000, v188
	v_cndmask_b32_e32 v186, v185, v186, vcc
	v_cmp_lt_i32_e32 vcc, v198, v187
	v_lshlrev_b32_e32 v202, 16, v192
	v_and_b32_e32 v203, 0xffff0000, v192
	v_cndmask_b32_e32 v187, v185, v198, vcc
	v_lshlrev_b32_e32 v198, 16, v188
	v_lshlrev_b32_e32 v188, 16, v189
	v_and_b32_e32 v189, 0xffff0000, v189
	v_lshlrev_b32_e32 v192, 16, v193
	v_and_b32_e32 v193, 0xffff0000, v193
	v_lshlrev_b32_e32 v200, 16, v190
	v_and_b32_e32 v201, 0xffff0000, v190
	v_lshlrev_b32_e32 v190, 16, v191
	v_and_b32_e32 v191, 0xffff0000, v191
	v_lshlrev_b32_e32 v204, 16, v194
	v_and_b32_e32 v205, 0xffff0000, v194
	v_lshlrev_b32_e32 v194, 16, v195
	v_and_b32_e32 v195, 0xffff0000, v195
	v_pk_add_f32 v[126:127], v[126:127], v[188:189]
	v_pk_add_f32 v[124:125], v[124:125], v[198:199]
	v_pk_add_f32 v[118:119], v[118:119], v[192:193]
	v_pk_add_f32 v[116:117], v[116:117], v[202:203]
	v_pk_add_f32 v[122:123], v[122:123], v[190:191]
	v_pk_add_f32 v[120:121], v[120:121], v[200:201]
	v_pk_add_f32 v[188:189], v[114:115], v[194:195]
	v_pk_add_f32 v[190:191], v[112:113], v[204:205]
	v_mul_f32_e32 v114, v125, v125
	v_mul_f32_e32 v115, v127, v127
	v_cvt_pk_bf16_f32 v112, v124, v125
	v_cvt_pk_bf16_f32 v113, v126, v127
	v_mul_f32_e32 v125, v117, v117
	v_mul_f32_e32 v127, v119, v119
	v_mul_f32_e32 v192, v121, v121
	v_mul_f32_e32 v194, v191, v191
	v_fmac_f32_e32 v114, v124, v124
	v_fmac_f32_e32 v115, v126, v126
	v_fmac_f32_e32 v125, v116, v116
	v_fmac_f32_e32 v127, v118, v118
	v_mul_f32_e32 v193, v123, v123
	v_mul_f32_e32 v195, v189, v189
	v_fmac_f32_e32 v192, v120, v120
	v_fmac_f32_e32 v194, v190, v190
	v_add_f32_e32 v114, v114, v115
	v_add_f32_e32 v115, v125, v127
	v_fmac_f32_e32 v193, v122, v122
	v_fmac_f32_e32 v195, v188, v188
	v_add_f32_e32 v114, v192, v114
	v_add_f32_e32 v115, v194, v115
	v_add_f32_e32 v114, v193, v114
	v_add_f32_e32 v115, v195, v115
	v_lshlrev_b32_e32 v186, 2, v186
	v_add_f32_e32 v124, v114, v115
	ds_bpermute_b32 v125, v186, v124
	v_cvt_pk_bf16_f32 v114, v120, v121
	v_cvt_pk_bf16_f32 v115, v122, v123
	global_store_dwordx4 v[196:197], v[112:115], off
	v_cvt_pk_bf16_f32 v116, v116, v117
	v_cvt_pk_bf16_f32 v117, v118, v119
	v_cvt_pk_bf16_f32 v118, v190, v191
	v_cvt_pk_bf16_f32 v119, v188, v189
	global_store_dwordx4 v[196:197], v[116:119], off offset:256
	s_waitcnt lgkmcnt(0)
	v_add_f32_e32 v113, v124, v125
	v_lshlrev_b32_e32 v112, 2, v187
	ds_bpermute_b32 v114, v112, v113
	s_and_saveexec_b64 s[38:39], s[4:5]
	s_cbranch_execz .LBB0_1927
	v_lshl_add_u64 v[116:117], v[166:167], 2, s[8:9]
	s_waitcnt lgkmcnt(0)
	v_add_f32_e32 v113, v113, v114
	global_atomic_add_f32 v[116:117], v113, off

.LBB0_1933:
	s_or_b64 exec, exec, s[38:39]
	v_add_u32_e32 v100, 0x80, v166
	v_ashrrev_i32_e32 v101, 31, v100
	s_waitcnt lgkmcnt(0)
	v_lshlrev_b64 v[64:65], 11, v[100:101]
	v_lshl_add_u64 v[64:65], s[12:13], 0, v[64:65]
	v_lshl_add_u64 v[110:111], v[64:65], 0, v[164:165]
	s_waitcnt vmcnt(12)
	v_mov_b32_e32 v102, v210
	v_mov_b32_e32 v103, v211
	v_mov_b32_e32 v104, v212
	v_mov_b32_e32 v105, v213
	v_mov_b32_e32 v106, v214
	v_mov_b32_e32 v107, v215
	v_mov_b32_e32 v108, v216
	v_mov_b32_e32 v109, v217
	v_add_u32_e32 v96, 0x90, v166
	v_add_u32_e32 v92, 0xa0, v166
	v_add_u32_e32 v88, 0xb0, v166
	v_ashrrev_i32_e32 v97, 31, v96
	v_ashrrev_i32_e32 v93, 31, v92
	v_ashrrev_i32_e32 v89, 31, v88
	v_lshlrev_b64 v[64:65], 11, v[96:97]
	v_lshlrev_b64 v[66:67], 11, v[92:93]
	v_lshlrev_b64 v[68:69], 11, v[88:89]
	v_lshl_add_u64 v[64:65], s[12:13], 0, v[64:65]
	v_lshl_add_u64 v[66:67], s[12:13], 0, v[66:67]
	v_lshl_add_u64 v[68:69], s[12:13], 0, v[68:69]
	v_lshl_add_u64 v[98:99], v[64:65], 0, v[164:165]
	v_lshl_add_u64 v[94:95], v[66:67], 0, v[164:165]
	v_lshl_add_u64 v[90:91], v[68:69], 0, v[164:165]
	v_mov_b32_e32 v84, v218
	v_mov_b32_e32 v85, v219
	v_mov_b32_e32 v86, v220
	v_mov_b32_e32 v87, v221
	v_mov_b32_e32 v80, v222
	v_mov_b32_e32 v81, v223
	v_mov_b32_e32 v82, v224
	v_mov_b32_e32 v83, v225
	v_mov_b32_e32 v76, v226
	v_mov_b32_e32 v77, v227
	v_mov_b32_e32 v78, v228
	v_mov_b32_e32 v79, v229
	v_mov_b32_e32 v72, v230
	v_mov_b32_e32 v73, v231
	v_mov_b32_e32 v74, v232
	v_mov_b32_e32 v75, v233
	v_mov_b32_e32 v68, v238
	v_mov_b32_e32 v69, v239
	v_mov_b32_e32 v70, v240
	v_mov_b32_e32 v71, v241
	v_mov_b32_e32 v64, v242
	v_mov_b32_e32 v65, v243
	v_mov_b32_e32 v66, v244
	v_mov_b32_e32 v67, v245
	v_lshlrev_b32_e32 v114, 16, v102
	v_and_b32_e32 v115, 0xffff0000, v102
	v_lshlrev_b32_e32 v102, 16, v103
	v_and_b32_e32 v103, 0xffff0000, v103
	v_lshlrev_b32_e32 v118, 16, v106
	v_and_b32_e32 v119, 0xffff0000, v106
	v_lshlrev_b32_e32 v106, 16, v107
	v_and_b32_e32 v107, 0xffff0000, v107
	v_lshlrev_b32_e32 v116, 16, v104
	v_and_b32_e32 v117, 0xffff0000, v104
	v_lshlrev_b32_e32 v104, 16, v105
	v_and_b32_e32 v105, 0xffff0000, v105
	v_lshlrev_b32_e32 v120, 16, v108
	v_and_b32_e32 v121, 0xffff0000, v108
	v_lshlrev_b32_e32 v108, 16, v109
	v_and_b32_e32 v109, 0xffff0000, v109
	v_pk_add_f32 v[62:63], v[62:63], v[102:103]
	v_pk_add_f32 v[60:61], v[60:61], v[114:115]
	v_pk_add_f32 v[54:55], v[54:55], v[106:107]
	v_pk_add_f32 v[52:53], v[52:53], v[118:119]
	v_pk_add_f32 v[58:59], v[58:59], v[104:105]
	v_pk_add_f32 v[56:57], v[56:57], v[116:117]
	v_pk_add_f32 v[102:103], v[50:51], v[108:109]
	v_pk_add_f32 v[104:105], v[48:49], v[120:121]
	v_mul_f32_e32 v50, v61, v61
	v_mul_f32_e32 v51, v63, v63
	v_cvt_pk_bf16_f32 v48, v60, v61
	v_cvt_pk_bf16_f32 v49, v62, v63
	v_mul_f32_e32 v61, v53, v53
	v_mul_f32_e32 v63, v55, v55
	v_mul_f32_e32 v106, v57, v57
	v_mul_f32_e32 v108, v105, v105
	v_fmac_f32_e32 v50, v60, v60
	v_fmac_f32_e32 v51, v62, v62
	v_fmac_f32_e32 v61, v52, v52
	v_fmac_f32_e32 v63, v54, v54
	v_mul_f32_e32 v107, v59, v59
	v_mul_f32_e32 v109, v103, v103
	v_fmac_f32_e32 v106, v56, v56
	v_fmac_f32_e32 v108, v104, v104
	v_add_f32_e32 v50, v50, v51
	v_add_f32_e32 v51, v61, v63
	v_fmac_f32_e32 v107, v58, v58
	v_fmac_f32_e32 v109, v102, v102
	v_add_f32_e32 v50, v106, v50
	v_add_f32_e32 v51, v108, v51
	v_add_f32_e32 v50, v107, v50
	v_add_f32_e32 v51, v109, v51
	v_add_f32_e32 v60, v50, v51
	ds_bpermute_b32 v61, v186, v60
	v_cvt_pk_bf16_f32 v50, v56, v57
	v_cvt_pk_bf16_f32 v51, v58, v59
	global_store_dwordx4 v[110:111], v[48:51], off
	s_waitcnt lgkmcnt(0)
	s_nop 0
	v_add_f32_e32 v48, v60, v61
	ds_bpermute_b32 v49, v112, v48
	v_cvt_pk_bf16_f32 v50, v52, v53
	v_cvt_pk_bf16_f32 v51, v54, v55
	v_cvt_pk_bf16_f32 v52, v104, v105
	v_cvt_pk_bf16_f32 v53, v102, v103
	global_store_dwordx4 v[110:111], v[50:53], off offset:256
	s_and_saveexec_b64 s[38:39], s[4:5]
	s_cbranch_execz .LBB0_1935
	v_lshl_add_u64 v[50:51], v[100:101], 2, s[8:9]
	s_waitcnt lgkmcnt(0)
	v_add_f32_e32 v48, v48, v49
	global_atomic_add_f32 v[50:51], v48, off
.LBB0_1935:
	s_or_b64 exec, exec, s[38:39]
	v_lshlrev_b32_e32 v48, 16, v84
	s_waitcnt lgkmcnt(0)
	v_and_b32_e32 v49, 0xffff0000, v84
	v_lshlrev_b32_e32 v50, 16, v85
	v_and_b32_e32 v51, 0xffff0000, v85
	v_lshlrev_b32_e32 v52, 16, v86
	v_and_b32_e32 v53, 0xffff0000, v86
	v_lshlrev_b32_e32 v54, 16, v87
	v_and_b32_e32 v55, 0xffff0000, v87
	v_pk_add_f32 v[46:47], v[46:47], v[50:51]
	v_pk_add_f32 v[44:45], v[44:45], v[48:49]
	v_pk_add_f32 v[48:49], v[42:43], v[54:55]
	v_pk_add_f32 v[42:43], v[40:41], v[52:53]
	v_mul_f32_e32 v40, v45, v45
	v_mul_f32_e32 v41, v47, v47
	v_fmac_f32_e32 v40, v44, v44
	v_fmac_f32_e32 v41, v46, v46
	v_add_f32_e32 v40, v40, v41
	v_mul_f32_e32 v41, v43, v43
	v_fmac_f32_e32 v41, v42, v42
	v_lshlrev_b32_e32 v56, 16, v80
	v_and_b32_e32 v57, 0xffff0000, v80
	v_lshlrev_b32_e32 v58, 16, v81
	v_and_b32_e32 v59, 0xffff0000, v81
	v_add_f32_e32 v40, v41, v40
	v_mul_f32_e32 v41, v49, v49
	v_lshlrev_b32_e32 v60, 16, v82
	v_and_b32_e32 v61, 0xffff0000, v82
	v_fmac_f32_e32 v41, v48, v48
	v_pk_add_f32 v[38:39], v[38:39], v[58:59]
	v_pk_add_f32 v[36:37], v[36:37], v[56:57]
	v_add_f32_e32 v50, v41, v40
	v_cvt_pk_bf16_f32 v40, v44, v45
	v_cvt_pk_bf16_f32 v41, v46, v47
	v_pk_add_f32 v[46:47], v[32:33], v[60:61]
	v_mul_f32_e32 v32, v37, v37
	v_mul_f32_e32 v33, v39, v39
	v_fmac_f32_e32 v32, v36, v36
	v_fmac_f32_e32 v33, v38, v38
	v_lshlrev_b32_e32 v62, 16, v83
	v_and_b32_e32 v63, 0xffff0000, v83
	v_add_f32_e32 v32, v32, v33
	v_mul_f32_e32 v33, v47, v47
	v_pk_add_f32 v[44:45], v[34:35], v[62:63]
	v_fmac_f32_e32 v33, v46, v46
	v_add_f32_e32 v32, v33, v32
	v_mul_f32_e32 v33, v45, v45
	v_fmac_f32_e32 v33, v44, v44
	v_add_f32_e32 v32, v33, v32
	v_add_f32_e32 v32, v50, v32
	ds_bpermute_b32 v33, v186, v32
	v_cvt_pk_bf16_f32 v42, v42, v43
	v_cvt_pk_bf16_f32 v43, v48, v49
	global_store_dwordx4 v[98:99], v[40:43], off
	v_cvt_pk_bf16_f32 v34, v36, v37
	s_waitcnt lgkmcnt(0)
	v_add_f32_e32 v32, v32, v33
	ds_bpermute_b32 v33, v112, v32
	v_cvt_pk_bf16_f32 v35, v38, v39
	v_cvt_pk_bf16_f32 v36, v46, v47
	v_cvt_pk_bf16_f32 v37, v44, v45
	global_store_dwordx4 v[98:99], v[34:37], off offset:256
	s_and_saveexec_b64 s[38:39], s[4:5]
	s_cbranch_execz .LBB0_1937
	v_lshl_add_u64 v[34:35], v[96:97], 2, s[8:9]
	s_waitcnt lgkmcnt(0)
	v_add_f32_e32 v32, v32, v33
	global_atomic_add_f32 v[34:35], v32, off
.LBB0_1937:
	s_or_b64 exec, exec, s[38:39]
	v_lshlrev_b32_e32 v32, 16, v76
	s_waitcnt lgkmcnt(0)
	v_and_b32_e32 v33, 0xffff0000, v76
	v_lshlrev_b32_e32 v34, 16, v77
	v_and_b32_e32 v35, 0xffff0000, v77
	v_lshlrev_b32_e32 v36, 16, v78
	v_and_b32_e32 v37, 0xffff0000, v78
	v_lshlrev_b32_e32 v38, 16, v79
	v_and_b32_e32 v39, 0xffff0000, v79
	v_pk_add_f32 v[30:31], v[30:31], v[34:35]
	v_pk_add_f32 v[28:29], v[28:29], v[32:33]
	v_pk_add_f32 v[32:33], v[26:27], v[38:39]
	v_pk_add_f32 v[26:27], v[24:25], v[36:37]
	v_mul_f32_e32 v24, v29, v29
	v_mul_f32_e32 v25, v31, v31
	v_fmac_f32_e32 v24, v28, v28
	v_fmac_f32_e32 v25, v30, v30
	v_add_f32_e32 v24, v24, v25
	v_mul_f32_e32 v25, v27, v27
	v_fmac_f32_e32 v25, v26, v26
	v_lshlrev_b32_e32 v40, 16, v72
	v_and_b32_e32 v41, 0xffff0000, v72
	v_lshlrev_b32_e32 v42, 16, v73
	v_and_b32_e32 v43, 0xffff0000, v73
	v_add_f32_e32 v24, v25, v24
	v_mul_f32_e32 v25, v33, v33
	v_lshlrev_b32_e32 v44, 16, v74
	v_and_b32_e32 v45, 0xffff0000, v74
	v_fmac_f32_e32 v25, v32, v32
	v_pk_add_f32 v[22:23], v[22:23], v[42:43]
	v_pk_add_f32 v[20:21], v[20:21], v[40:41]
	v_add_f32_e32 v34, v25, v24
	v_cvt_pk_bf16_f32 v24, v28, v29
	v_cvt_pk_bf16_f32 v25, v30, v31
	v_pk_add_f32 v[30:31], v[16:17], v[44:45]
	v_mul_f32_e32 v16, v21, v21
	v_mul_f32_e32 v17, v23, v23
	v_fmac_f32_e32 v16, v20, v20
	v_fmac_f32_e32 v17, v22, v22
	v_lshlrev_b32_e32 v46, 16, v75
	v_and_b32_e32 v47, 0xffff0000, v75
	v_add_f32_e32 v16, v16, v17
	v_mul_f32_e32 v17, v31, v31
	v_pk_add_f32 v[28:29], v[18:19], v[46:47]
	v_fmac_f32_e32 v17, v30, v30
	v_add_f32_e32 v16, v17, v16
	v_mul_f32_e32 v17, v29, v29
	v_fmac_f32_e32 v17, v28, v28
	v_add_f32_e32 v16, v17, v16
	v_add_f32_e32 v16, v34, v16
	ds_bpermute_b32 v17, v186, v16
	v_cvt_pk_bf16_f32 v26, v26, v27
	v_cvt_pk_bf16_f32 v27, v32, v33
	global_store_dwordx4 v[94:95], v[24:27], off
	v_cvt_pk_bf16_f32 v18, v20, v21
	s_waitcnt lgkmcnt(0)
	v_add_f32_e32 v16, v16, v17
	ds_bpermute_b32 v17, v112, v16
	v_cvt_pk_bf16_f32 v19, v22, v23
	v_cvt_pk_bf16_f32 v20, v30, v31
	v_cvt_pk_bf16_f32 v21, v28, v29
	global_store_dwordx4 v[94:95], v[18:21], off offset:256
	s_and_saveexec_b64 s[38:39], s[4:5]
	s_cbranch_execz .LBB0_1939
	v_lshl_add_u64 v[18:19], v[92:93], 2, s[8:9]
	s_waitcnt lgkmcnt(0)
	v_add_f32_e32 v16, v16, v17
	global_atomic_add_f32 v[18:19], v16, off
.LBB0_1939:
	s_or_b64 exec, exec, s[38:39]
	v_lshlrev_b32_e32 v16, 16, v68
	s_waitcnt lgkmcnt(0)
	v_and_b32_e32 v17, 0xffff0000, v68
	v_lshlrev_b32_e32 v18, 16, v69
	v_and_b32_e32 v19, 0xffff0000, v69
	v_lshlrev_b32_e32 v20, 16, v70
	v_and_b32_e32 v21, 0xffff0000, v70
	v_lshlrev_b32_e32 v22, 16, v71
	v_and_b32_e32 v23, 0xffff0000, v71
	v_pk_add_f32 v[14:15], v[14:15], v[18:19]
	v_pk_add_f32 v[12:13], v[12:13], v[16:17]
	v_pk_add_f32 v[16:17], v[10:11], v[22:23]
	v_pk_add_f32 v[10:11], v[8:9], v[20:21]
	v_mul_f32_e32 v8, v13, v13
	v_mul_f32_e32 v9, v15, v15
	v_fmac_f32_e32 v8, v12, v12
	v_fmac_f32_e32 v9, v14, v14
	v_add_f32_e32 v8, v8, v9
	v_mul_f32_e32 v9, v11, v11
	v_fmac_f32_e32 v9, v10, v10
	v_lshlrev_b32_e32 v24, 16, v64
	v_and_b32_e32 v25, 0xffff0000, v64
	v_lshlrev_b32_e32 v26, 16, v65
	v_and_b32_e32 v27, 0xffff0000, v65
	v_add_f32_e32 v8, v9, v8
	v_mul_f32_e32 v9, v17, v17
	v_lshlrev_b32_e32 v28, 16, v66
	v_and_b32_e32 v29, 0xffff0000, v66
	v_fmac_f32_e32 v9, v16, v16
	v_pk_add_f32 v[6:7], v[6:7], v[26:27]
	v_pk_add_f32 v[4:5], v[4:5], v[24:25]
	v_add_f32_e32 v18, v9, v8
	v_cvt_pk_bf16_f32 v8, v12, v13
	v_cvt_pk_bf16_f32 v9, v14, v15
	v_pk_add_f32 v[14:15], v[0:1], v[28:29]
	v_mul_f32_e32 v0, v5, v5
	v_mul_f32_e32 v1, v7, v7
	v_fmac_f32_e32 v0, v4, v4
	v_fmac_f32_e32 v1, v6, v6
	v_lshlrev_b32_e32 v30, 16, v67
	v_and_b32_e32 v31, 0xffff0000, v67
	v_add_f32_e32 v0, v0, v1
	v_mul_f32_e32 v1, v15, v15
	v_pk_add_f32 v[12:13], v[2:3], v[30:31]
	v_fmac_f32_e32 v1, v14, v14
	v_add_f32_e32 v0, v1, v0
	v_mul_f32_e32 v1, v13, v13
	v_fmac_f32_e32 v1, v12, v12
	v_add_f32_e32 v0, v1, v0
	v_add_f32_e32 v0, v18, v0
	ds_bpermute_b32 v1, v186, v0
	v_cvt_pk_bf16_f32 v10, v10, v11
	v_cvt_pk_bf16_f32 v11, v16, v17
	global_store_dwordx4 v[90:91], v[8:11], off
	v_cvt_pk_bf16_f32 v2, v4, v5
	s_waitcnt lgkmcnt(0)
	v_add_f32_e32 v0, v0, v1
	ds_bpermute_b32 v1, v112, v0
	v_cvt_pk_bf16_f32 v3, v6, v7
	v_cvt_pk_bf16_f32 v4, v14, v15
	v_cvt_pk_bf16_f32 v5, v12, v13
	global_store_dwordx4 v[90:91], v[2:5], off offset:256
	s_and_saveexec_b64 s[38:39], s[4:5]
	s_cbranch_execz .LBB0_1941
	v_lshl_add_u64 v[2:3], v[88:89], 2, s[8:9]
	s_waitcnt lgkmcnt(0)
	v_add_f32_e32 v0, v0, v1
	global_atomic_add_f32 v[2:3], v0, off

.LBB0_2041:
	v_readlane_b32 s0, v236, 8
	v_lshrrev_b32_e32 v128, 1, v182
	s_lshl_b32 s4, s0, 8
	v_and_b32_e32 v128, 24, v128
	s_add_i32 s0, s4, s2
	v_lshl_or_b32 v128, s47, 8, v128
	v_or_b32_e32 v158, s0, v172
	v_or_b32_e32 v160, s43, v128
	v_ashrrev_i32_e32 v159, 31, v158
	v_ashrrev_i32_e32 v161, 31, v160
	v_lshlrev_b64 v[128:129], 11, v[158:159]
	v_lshl_add_u64 v[128:129], s[12:13], 0, v[128:129]
	v_lshlrev_b64 v[170:171], 1, v[160:161]
	v_lshl_add_u64 v[128:129], v[128:129], 0, v[170:171]
	s_barrier
	global_load_dwordx4 v[162:165], v[128:129], off
	global_load_dwordx4 v[166:169], v[128:129], off offset:256
	s_mov_b64 s[98:99], 0x40000
	v_lshl_add_u64 v[222:223], v[128:129], 0, s[98:99]
	s_mov_b64 s[98:99], 0x8000
	v_or_b32_e32 v156, 16, v158
	v_or_b32_e32 v154, 32, v158
	v_or_b32_e32 v152, 48, v158
	v_ashrrev_i32_e32 v157, 31, v156
	v_ashrrev_i32_e32 v155, 31, v154
	v_ashrrev_i32_e32 v153, 31, v152
	v_lshlrev_b64 v[128:129], 11, v[156:157]
	v_lshlrev_b64 v[130:131], 11, v[154:155]
	v_lshlrev_b64 v[132:133], 11, v[152:153]
	v_lshl_add_u64 v[128:129], s[12:13], 0, v[128:129]
	v_lshl_add_u64 v[130:131], s[12:13], 0, v[130:131]
	v_lshl_add_u64 v[132:133], s[12:13], 0, v[132:133]
	v_lshl_add_u64 v[128:129], v[128:129], 0, v[170:171]
	v_lshl_add_u64 v[130:131], v[130:131], 0, v[170:171]
	v_lshl_add_u64 v[174:175], v[132:133], 0, v[170:171]
	global_load_dwordx4 v[148:151], v[128:129], off
	global_load_dwordx4 v[144:147], v[128:129], off offset:256
	global_load_dwordx4 v[140:143], v[130:131], off
	global_load_dwordx4 v[136:139], v[130:131], off offset:256
	global_load_dwordx4 v[132:135], v[174:175], off
	s_nop 0
	global_load_dwordx4 v[128:131], v[174:175], off offset:256
	global_load_dwordx4 v[190:193], v[222:223], off
	global_load_dwordx4 v[194:197], v[222:223], off offset:256
	v_lshl_add_u64 v[222:223], v[222:223], 0, s[98:99]
	global_load_dwordx4 v[198:201], v[222:223], off
	global_load_dwordx4 v[202:205], v[222:223], off offset:256
	v_lshl_add_u64 v[222:223], v[222:223], 0, s[98:99]
	global_load_dwordx4 v[206:209], v[222:223], off
	global_load_dwordx4 v[210:213], v[222:223], off offset:256
	v_lshl_add_u64 v[222:223], v[222:223], 0, s[98:99]
	global_load_dwordx4 v[214:217], v[222:223], off
	global_load_dwordx4 v[218:221], v[222:223], off offset:256
	v_mbcnt_lo_u32_b32 v174, -1, 0
	v_mbcnt_hi_u32_b32 v175, -1, v174
	v_and_b32_e32 v176, 64, v175
	v_add_u32_e32 v184, 64, v176
	v_and_b32_e32 v173, 63, v182
	v_xor_b32_e32 v174, 16, v175
	v_cmp_lt_i32_e64 s[0:1], v174, v184
	v_cmp_gt_u32_e32 vcc, 16, v173
	s_waitcnt vmcnt(8)
	v_lshlrev_b32_e32 v176, 16, v162
	v_and_b32_e32 v177, 0xffff0000, v162
	v_lshlrev_b32_e32 v162, 16, v163
	v_and_b32_e32 v163, 0xffff0000, v163
	v_lshlrev_b32_e32 v178, 16, v164
	v_and_b32_e32 v179, 0xffff0000, v164
	v_pk_add_f32 v[176:177], v[176:177], 0 op_sel_hi:[1,0]
	v_pk_add_f32 v[162:163], v[162:163], 0 op_sel_hi:[1,0]
	v_lshlrev_b32_e32 v164, 16, v165
	v_and_b32_e32 v165, 0xffff0000, v165
	v_lshlrev_b32_e32 v180, 16, v166
	v_and_b32_e32 v181, 0xffff0000, v166
	v_lshlrev_b32_e32 v166, 16, v167
	v_and_b32_e32 v167, 0xffff0000, v167
	v_pk_add_f32 v[178:179], v[178:179], 0 op_sel_hi:[1,0]
	v_pk_add_f32 v[126:127], v[126:127], v[162:163]
	v_pk_add_f32 v[124:125], v[124:125], v[176:177]
	v_lshlrev_b32_e32 v182, 16, v168
	v_and_b32_e32 v183, 0xffff0000, v168
	v_pk_add_f32 v[164:165], v[164:165], 0 op_sel_hi:[1,0]
	v_pk_add_f32 v[180:181], v[180:181], 0 op_sel_hi:[1,0]
	v_pk_add_f32 v[166:167], v[166:167], 0 op_sel_hi:[1,0]
	v_pk_add_f32 v[120:121], v[120:121], v[178:179]
	v_mul_f32_e32 v162, v125, v125
	v_mul_f32_e32 v163, v127, v127
	v_pk_add_f32 v[182:183], v[182:183], 0 op_sel_hi:[1,0]
	v_pk_add_f32 v[122:123], v[122:123], v[164:165]
	v_pk_add_f32 v[118:119], v[118:119], v[166:167]
	v_pk_add_f32 v[116:117], v[116:117], v[180:181]
	v_mul_f32_e32 v164, v121, v121
	v_fmac_f32_e32 v162, v124, v124
	v_fmac_f32_e32 v163, v126, v126
	v_lshlrev_b32_e32 v168, 16, v169
	v_and_b32_e32 v169, 0xffff0000, v169
	v_pk_add_f32 v[112:113], v[112:113], v[182:183]
	v_mul_f32_e32 v166, v117, v117
	v_mul_f32_e32 v167, v119, v119
	v_fmac_f32_e32 v164, v120, v120
	v_add_f32_e32 v162, v162, v163
	v_pk_add_f32 v[168:169], v[168:169], 0 op_sel_hi:[1,0]
	v_fmac_f32_e32 v166, v116, v116
	v_fmac_f32_e32 v167, v118, v118
	v_add_f32_e32 v162, v164, v162
	v_mul_f32_e32 v164, v113, v113
	v_pk_add_f32 v[114:115], v[114:115], v[168:169]
	v_add_f32_e32 v163, v166, v167
	v_fmac_f32_e32 v164, v112, v112
	v_mul_f32_e32 v165, v123, v123
	v_add_f32_e32 v163, v164, v163
	v_mul_f32_e32 v164, v115, v115
	v_fmac_f32_e32 v165, v122, v122
	v_fmac_f32_e32 v164, v114, v114
	v_cndmask_b32_e64 v174, v175, v174, s[0:1]
	v_add_f32_e32 v162, v165, v162
	v_add_f32_e32 v163, v164, v163
	v_lshlrev_b32_e32 v174, 2, v174
	v_add_f32_e32 v162, v162, v163
	ds_bpermute_b32 v163, v174, v162
	v_xor_b32_e32 v164, 32, v175
	v_cmp_lt_i32_e64 s[0:1], v164, v184
	s_waitcnt lgkmcnt(0)
	v_add_f32_e32 v162, v162, v163
	v_cndmask_b32_e64 v164, v175, v164, s[0:1]
	v_lshlrev_b32_e32 v175, 2, v164
	ds_bpermute_b32 v163, v175, v162
	s_and_saveexec_b64 s[0:1], vcc
	s_cbranch_execz .LBB0_2043
	v_lshl_add_u64 v[164:165], v[158:159], 2, s[8:9]
	s_waitcnt lgkmcnt(0)
	v_add_f32_e32 v162, v162, v163
	global_atomic_add_f32 v[164:165], v162, off

.LBB0_2049:
	s_or_b64 exec, exec, s[0:1]
	v_add_u32_e32 v168, 0x80, v158
	v_ashrrev_i32_e32 v169, 31, v168
	s_waitcnt lgkmcnt(0)
	v_lshlrev_b64 v[64:65], 11, v[168:169]
	v_lshl_add_u64 v[64:65], s[12:13], 0, v[64:65]
	v_lshl_add_u64 v[64:65], v[64:65], 0, v[170:171]
	s_waitcnt vmcnt(4)
	v_mov_b32_e32 v176, v190
	v_mov_b32_e32 v177, v191
	v_mov_b32_e32 v178, v192
	v_mov_b32_e32 v179, v193
	v_mov_b32_e32 v180, v194
	v_mov_b32_e32 v181, v195
	v_mov_b32_e32 v182, v196
	v_mov_b32_e32 v183, v197
	v_add_u32_e32 v128, 0x90, v158
	v_add_u32_e32 v90, 0xa0, v158
	v_add_u32_e32 v88, 0xb0, v158
	v_ashrrev_i32_e32 v129, 31, v128
	v_ashrrev_i32_e32 v91, 31, v90
	v_ashrrev_i32_e32 v89, 31, v88
	v_lshlrev_b64 v[64:65], 11, v[128:129]
	v_lshlrev_b64 v[66:67], 11, v[90:91]
	v_lshlrev_b64 v[68:69], 11, v[88:89]
	v_lshl_add_u64 v[64:65], s[12:13], 0, v[64:65]
	v_lshl_add_u64 v[66:67], s[12:13], 0, v[66:67]
	v_lshl_add_u64 v[68:69], s[12:13], 0, v[68:69]
	v_lshl_add_u64 v[64:65], v[64:65], 0, v[170:171]
	v_lshl_add_u64 v[66:67], v[66:67], 0, v[170:171]
	v_lshl_add_u64 v[170:171], v[68:69], 0, v[170:171]
	v_mov_b32_e32 v84, v198
	v_mov_b32_e32 v85, v199
	v_mov_b32_e32 v86, v200
	v_mov_b32_e32 v87, v201
	v_mov_b32_e32 v80, v202
	v_mov_b32_e32 v81, v203
	v_mov_b32_e32 v82, v204
	v_mov_b32_e32 v83, v205
	v_mov_b32_e32 v76, v206
	v_mov_b32_e32 v77, v207
	v_mov_b32_e32 v78, v208
	v_mov_b32_e32 v79, v209
	v_mov_b32_e32 v72, v210
	v_mov_b32_e32 v73, v211
	v_mov_b32_e32 v74, v212
	v_mov_b32_e32 v75, v213
	v_mov_b32_e32 v68, v214
	v_mov_b32_e32 v69, v215
	v_mov_b32_e32 v70, v216
	v_mov_b32_e32 v71, v217
	s_nop 0
	v_mov_b32_e32 v64, v218
	v_mov_b32_e32 v65, v219
	v_mov_b32_e32 v66, v220
	v_mov_b32_e32 v67, v221
	v_lshlrev_b32_e32 v170, 16, v176
	v_and_b32_e32 v171, 0xffff0000, v176
	v_lshlrev_b32_e32 v176, 16, v177
	v_and_b32_e32 v177, 0xffff0000, v177
	v_lshlrev_b32_e32 v186, 16, v180
	v_and_b32_e32 v187, 0xffff0000, v180
	v_lshlrev_b32_e32 v180, 16, v181
	v_and_b32_e32 v181, 0xffff0000, v181
	v_lshlrev_b32_e32 v184, 16, v178
	v_and_b32_e32 v185, 0xffff0000, v178
	v_lshlrev_b32_e32 v178, 16, v179
	v_and_b32_e32 v179, 0xffff0000, v179
	v_lshlrev_b32_e32 v188, 16, v182
	v_and_b32_e32 v189, 0xffff0000, v182
	v_pk_add_f32 v[170:171], v[170:171], 0 op_sel_hi:[1,0]
	v_pk_add_f32 v[176:177], v[176:177], 0 op_sel_hi:[1,0]
	v_pk_add_f32 v[186:187], v[186:187], 0 op_sel_hi:[1,0]
	v_pk_add_f32 v[180:181], v[180:181], 0 op_sel_hi:[1,0]
	v_lshlrev_b32_e32 v182, 16, v183
	v_and_b32_e32 v183, 0xffff0000, v183
	v_pk_add_f32 v[184:185], v[184:185], 0 op_sel_hi:[1,0]
	v_pk_add_f32 v[178:179], v[178:179], 0 op_sel_hi:[1,0]
	v_pk_add_f32 v[188:189], v[188:189], 0 op_sel_hi:[1,0]
	v_pk_add_f32 v[62:63], v[62:63], v[176:177]
	v_pk_add_f32 v[60:61], v[60:61], v[170:171]
	v_pk_add_f32 v[54:55], v[54:55], v[180:181]
	v_pk_add_f32 v[52:53], v[52:53], v[186:187]
	v_pk_add_f32 v[182:183], v[182:183], 0 op_sel_hi:[1,0]
	v_pk_add_f32 v[58:59], v[58:59], v[178:179]
	v_pk_add_f32 v[56:57], v[56:57], v[184:185]
	v_pk_add_f32 v[48:49], v[48:49], v[188:189]
	v_mul_f32_e32 v170, v61, v61
	v_mul_f32_e32 v171, v63, v63
	v_mul_f32_e32 v178, v53, v53
	v_mul_f32_e32 v179, v55, v55
	v_pk_add_f32 v[50:51], v[50:51], v[182:183]
	v_mul_f32_e32 v176, v57, v57
	v_mul_f32_e32 v180, v49, v49
	v_fmac_f32_e32 v170, v60, v60
	v_fmac_f32_e32 v171, v62, v62
	v_fmac_f32_e32 v178, v52, v52
	v_fmac_f32_e32 v179, v54, v54
	v_mul_f32_e32 v177, v59, v59
	v_mul_f32_e32 v181, v51, v51
	v_fmac_f32_e32 v176, v56, v56
	v_fmac_f32_e32 v180, v48, v48
	v_add_f32_e32 v170, v170, v171
	v_add_f32_e32 v171, v178, v179
	v_fmac_f32_e32 v177, v58, v58
	v_fmac_f32_e32 v181, v50, v50
	v_add_f32_e32 v170, v176, v170
	v_add_f32_e32 v171, v180, v171
	v_add_f32_e32 v170, v177, v170
	v_add_f32_e32 v171, v181, v171
	v_add_f32_e32 v170, v170, v171
	ds_bpermute_b32 v171, v174, v170
	s_waitcnt lgkmcnt(0)
	v_add_f32_e32 v170, v170, v171
	ds_bpermute_b32 v171, v175, v170
	s_and_saveexec_b64 s[0:1], vcc
	s_cbranch_execz .LBB0_2051
	v_lshl_add_u64 v[176:177], v[168:169], 2, s[8:9]
	s_waitcnt lgkmcnt(0)
	v_add_f32_e32 v170, v170, v171
	global_atomic_add_f32 v[176:177], v170, off
.LBB0_2051:
	s_or_b64 exec, exec, s[0:1]
	v_lshlrev_b32_e32 v170, 16, v84
	s_waitcnt lgkmcnt(0)
	v_and_b32_e32 v171, 0xffff0000, v84
	v_lshlrev_b32_e32 v84, 16, v85
	v_and_b32_e32 v85, 0xffff0000, v85
	v_lshlrev_b32_e32 v176, 16, v86
	v_and_b32_e32 v177, 0xffff0000, v86
	v_pk_add_f32 v[170:171], v[170:171], 0 op_sel_hi:[1,0]
	v_pk_add_f32 v[84:85], v[84:85], 0 op_sel_hi:[1,0]
	v_pk_add_f32 v[44:45], v[44:45], v[170:171]
	v_pk_add_f32 v[46:47], v[46:47], v[84:85]
	v_pk_add_f32 v[84:85], v[176:177], 0 op_sel_hi:[1,0]
	v_lshlrev_b32_e32 v86, 16, v87
	v_pk_add_f32 v[40:41], v[40:41], v[84:85]
	v_mul_f32_e32 v84, v45, v45
	v_mul_f32_e32 v85, v47, v47
	v_and_b32_e32 v87, 0xffff0000, v87
	v_fmac_f32_e32 v84, v44, v44
	v_fmac_f32_e32 v85, v46, v46
	v_pk_add_f32 v[86:87], v[86:87], 0 op_sel_hi:[1,0]
	v_add_f32_e32 v84, v84, v85
	v_mul_f32_e32 v85, v41, v41
	v_pk_add_f32 v[42:43], v[42:43], v[86:87]
	v_fmac_f32_e32 v85, v40, v40
	v_add_f32_e32 v84, v85, v84
	v_mul_f32_e32 v85, v43, v43
	v_fmac_f32_e32 v85, v42, v42
	v_add_f32_e32 v170, v85, v84
	v_lshlrev_b32_e32 v84, 16, v80
	v_and_b32_e32 v85, 0xffff0000, v80
	v_lshlrev_b32_e32 v80, 16, v81
	v_and_b32_e32 v81, 0xffff0000, v81
	v_lshlrev_b32_e32 v86, 16, v82
	v_and_b32_e32 v87, 0xffff0000, v82
	v_pk_add_f32 v[84:85], v[84:85], 0 op_sel_hi:[1,0]
	v_pk_add_f32 v[80:81], v[80:81], 0 op_sel_hi:[1,0]
	v_pk_add_f32 v[36:37], v[36:37], v[84:85]
	v_pk_add_f32 v[38:39], v[38:39], v[80:81]
	v_pk_add_f32 v[80:81], v[86:87], 0 op_sel_hi:[1,0]
	v_lshlrev_b32_e32 v82, 16, v83
	v_pk_add_f32 v[28:29], v[28:29], v[80:81]
	v_mul_f32_e32 v80, v37, v37
	v_mul_f32_e32 v81, v39, v39
	v_and_b32_e32 v83, 0xffff0000, v83
	v_fmac_f32_e32 v80, v36, v36
	v_fmac_f32_e32 v81, v38, v38
	v_pk_add_f32 v[82:83], v[82:83], 0 op_sel_hi:[1,0]
	v_add_f32_e32 v80, v80, v81
	v_mul_f32_e32 v81, v29, v29
	v_pk_add_f32 v[30:31], v[30:31], v[82:83]
	v_fmac_f32_e32 v81, v28, v28
	v_add_f32_e32 v80, v81, v80
	v_mul_f32_e32 v81, v31, v31
	v_fmac_f32_e32 v81, v30, v30
	v_add_f32_e32 v80, v81, v80
	v_add_f32_e32 v80, v170, v80
	ds_bpermute_b32 v81, v174, v80
	s_waitcnt lgkmcnt(0)
	v_add_f32_e32 v80, v80, v81
	ds_bpermute_b32 v81, v175, v80
	s_and_saveexec_b64 s[0:1], vcc
	s_cbranch_execz .LBB0_2053
	v_lshl_add_u64 v[82:83], v[128:129], 2, s[8:9]
	s_waitcnt lgkmcnt(0)
	v_add_f32_e32 v80, v80, v81
	global_atomic_add_f32 v[82:83], v80, off
.LBB0_2053:
	s_or_b64 exec, exec, s[0:1]
	v_lshlrev_b32_e32 v80, 16, v76
	s_waitcnt lgkmcnt(0)
	v_and_b32_e32 v81, 0xffff0000, v76
	v_lshlrev_b32_e32 v76, 16, v77
	v_and_b32_e32 v77, 0xffff0000, v77
	v_lshlrev_b32_e32 v82, 16, v78
	v_and_b32_e32 v83, 0xffff0000, v78
	v_pk_add_f32 v[80:81], v[80:81], 0 op_sel_hi:[1,0]
	v_pk_add_f32 v[76:77], v[76:77], 0 op_sel_hi:[1,0]
	v_pk_add_f32 v[32:33], v[32:33], v[80:81]
	v_pk_add_f32 v[34:35], v[34:35], v[76:77]
	v_pk_add_f32 v[76:77], v[82:83], 0 op_sel_hi:[1,0]
	v_lshlrev_b32_e32 v78, 16, v79
	v_pk_add_f32 v[24:25], v[24:25], v[76:77]
	v_mul_f32_e32 v76, v33, v33
	v_mul_f32_e32 v77, v35, v35
	v_and_b32_e32 v79, 0xffff0000, v79
	v_fmac_f32_e32 v76, v32, v32
	v_fmac_f32_e32 v77, v34, v34
	v_pk_add_f32 v[78:79], v[78:79], 0 op_sel_hi:[1,0]
	v_add_f32_e32 v76, v76, v77
	v_mul_f32_e32 v77, v25, v25
	v_pk_add_f32 v[26:27], v[26:27], v[78:79]
	v_fmac_f32_e32 v77, v24, v24
	v_add_f32_e32 v76, v77, v76
	v_mul_f32_e32 v77, v27, v27
	v_fmac_f32_e32 v77, v26, v26
	v_add_f32_e32 v80, v77, v76
	v_lshlrev_b32_e32 v76, 16, v72
	v_and_b32_e32 v77, 0xffff0000, v72
	v_lshlrev_b32_e32 v72, 16, v73
	v_and_b32_e32 v73, 0xffff0000, v73
	v_lshlrev_b32_e32 v78, 16, v74
	v_and_b32_e32 v79, 0xffff0000, v74
	v_pk_add_f32 v[76:77], v[76:77], 0 op_sel_hi:[1,0]
	v_pk_add_f32 v[72:73], v[72:73], 0 op_sel_hi:[1,0]
	v_lshlrev_b32_e32 v74, 16, v75
	v_and_b32_e32 v75, 0xffff0000, v75
	v_pk_add_f32 v[22:23], v[22:23], v[72:73]
	v_pk_add_f32 v[72:73], v[20:21], v[76:77]
	v_pk_add_f32 v[76:77], v[78:79], 0 op_sel_hi:[1,0]
	v_pk_add_f32 v[20:21], v[74:75], 0 op_sel_hi:[1,0]
	v_pk_add_f32 v[74:75], v[12:13], v[76:77]
	v_mul_f32_e32 v12, v73, v73
	v_mul_f32_e32 v13, v23, v23
	v_fmac_f32_e32 v12, v72, v72
	v_fmac_f32_e32 v13, v22, v22
	v_add_f32_e32 v12, v12, v13
	v_mul_f32_e32 v13, v75, v75
	v_pk_add_f32 v[20:21], v[14:15], v[20:21]
	v_fmac_f32_e32 v13, v74, v74
	v_add_f32_e32 v12, v13, v12
	v_mul_f32_e32 v13, v21, v21
	v_fmac_f32_e32 v13, v20, v20
	v_add_f32_e32 v12, v13, v12
	v_add_f32_e32 v12, v80, v12
	ds_bpermute_b32 v13, v174, v12
	s_waitcnt lgkmcnt(0)
	v_add_f32_e32 v12, v12, v13
	ds_bpermute_b32 v13, v175, v12
	s_and_saveexec_b64 s[0:1], vcc
	s_cbranch_execz .LBB0_2055
	v_lshl_add_u64 v[14:15], v[90:91], 2, s[8:9]
	s_waitcnt lgkmcnt(0)
	v_add_f32_e32 v12, v12, v13
	global_atomic_add_f32 v[14:15], v12, off
.LBB0_2055:
	s_or_b64 exec, exec, s[0:1]
	v_lshlrev_b32_e32 v12, 16, v68
	s_waitcnt lgkmcnt(0)
	v_and_b32_e32 v13, 0xffff0000, v68
	v_lshlrev_b32_e32 v14, 16, v69
	v_and_b32_e32 v15, 0xffff0000, v69
	v_lshlrev_b32_e32 v68, 16, v70
	v_and_b32_e32 v69, 0xffff0000, v70
	v_pk_add_f32 v[12:13], v[12:13], 0 op_sel_hi:[1,0]
	v_pk_add_f32 v[14:15], v[14:15], 0 op_sel_hi:[1,0]
	v_lshlrev_b32_e32 v76, 16, v71
	v_and_b32_e32 v77, 0xffff0000, v71
	v_pk_add_f32 v[18:19], v[18:19], v[14:15]
	v_pk_add_f32 v[70:71], v[16:17], v[12:13]
	v_pk_add_f32 v[12:13], v[68:69], 0 op_sel_hi:[1,0]
	v_pk_add_f32 v[14:15], v[76:77], 0 op_sel_hi:[1,0]
	v_pk_add_f32 v[68:69], v[8:9], v[12:13]
	v_mul_f32_e32 v8, v71, v71
	v_mul_f32_e32 v9, v19, v19
	v_fmac_f32_e32 v8, v70, v70
	v_fmac_f32_e32 v9, v18, v18
	v_add_f32_e32 v8, v8, v9
	v_mul_f32_e32 v9, v69, v69
	v_pk_add_f32 v[16:17], v[10:11], v[14:15]
	v_fmac_f32_e32 v9, v68, v68
	v_add_f32_e32 v8, v9, v8
	v_mul_f32_e32 v9, v17, v17
	v_fmac_f32_e32 v9, v16, v16
	v_add_f32_e32 v80, v9, v8
	v_lshlrev_b32_e32 v8, 16, v64
	v_and_b32_e32 v9, 0xffff0000, v64
	v_lshlrev_b32_e32 v10, 16, v65
	v_and_b32_e32 v11, 0xffff0000, v65
	v_lshlrev_b32_e32 v12, 16, v66
	v_and_b32_e32 v13, 0xffff0000, v66
	v_pk_add_f32 v[8:9], v[8:9], 0 op_sel_hi:[1,0]
	v_pk_add_f32 v[10:11], v[10:11], 0 op_sel_hi:[1,0]
	v_pk_add_f32 v[76:77], v[4:5], v[8:9]
	v_pk_add_f32 v[64:65], v[6:7], v[10:11]
	v_pk_add_f32 v[4:5], v[12:13], 0 op_sel_hi:[1,0]
	v_lshlrev_b32_e32 v14, 16, v67
	v_pk_add_f32 v[78:79], v[0:1], v[4:5]
	v_mul_f32_e32 v0, v77, v77
	v_mul_f32_e32 v1, v65, v65
	v_and_b32_e32 v15, 0xffff0000, v67
	v_fmac_f32_e32 v0, v76, v76
	v_fmac_f32_e32 v1, v64, v64
	v_pk_add_f32 v[6:7], v[14:15], 0 op_sel_hi:[1,0]
	v_add_f32_e32 v0, v0, v1
	v_mul_f32_e32 v1, v79, v79
	v_pk_add_f32 v[66:67], v[2:3], v[6:7]
	v_fmac_f32_e32 v1, v78, v78
	v_add_f32_e32 v0, v1, v0
	v_mul_f32_e32 v1, v67, v67
	v_fmac_f32_e32 v1, v66, v66
	v_add_f32_e32 v0, v1, v0
	v_add_f32_e32 v0, v80, v0
	ds_bpermute_b32 v1, v174, v0
	s_waitcnt lgkmcnt(0)
	v_add_f32_e32 v0, v0, v1
	ds_bpermute_b32 v1, v175, v0
	s_and_saveexec_b64 s[0:1], vcc
	s_cbranch_execz .LBB0_2057
	v_lshl_add_u64 v[2:3], v[88:89], 2, s[8:9]
	s_waitcnt lgkmcnt(0)
	v_add_f32_e32 v0, v0, v1
	global_atomic_add_f32 v[2:3], v0, off
